# tile coordinates in closed form (no integer division per tile) in six GEMM phases; conv epilogue row rotates read their source directly (130 copies removed)
# speedup vs baseline: 1.0088x; 1.0071x over previous
;     __host__ __device__ bool next(int i, Unit& u) const {
;     ...
;         int wgid = (int)L; { const int q = nwg / NXCD, r = nwg % NXCD, xcd = wgid % NXCD, off = wgid / NXCD; wgid = (xcd < r ? xcd * (q + 1) : r * (q + 1) + (xcd - r) * q) + off; }
;         const int nig = WGM * nN, gid = wgid / nig, fm = gid * WGM, gsz = (nM - fm) < WGM ? (nM - fm) : WGM;
;         u.pm = fm + ((wgid % nig) % gsz); u.pn = (wgid % nig) / gsz; return true;
.LBB0_126:
	s_ashr_i32 s22, s24, 3
	s_add_i32 s22, s26, s22
	s_ashr_i32 s23, s22, 31
	s_lshr_b32 s23, s23, 24
	s_add_i32 s23, s22, s23
	s_ashr_i32 s24, s23, 8
	s_lshl_b32 s24, s24, 3
	s_and_b32 s23, s23, 0xffffff00
	s_sub_i32 s23, s22, s23
	s_lshr_b32 s22, s23, 3
	s_and_b32 s23, s23, 7
	s_add_i32 s24, s24, s23
	s_mov_b64 s[26:27], -1
	s_branch .LBB0_128

; __device__ __forceinline__ unsigned cvt_pk_bf16(float lo, float hi) { f32x2 v = {lo, hi}; return __builtin_bit_cast(unsigned, __builtin_convertvector(v, bf2_t)); }
;     template <int CTRL> static __device__ __forceinline__ f32x4 rorv(const f32x4 v) { f32x4 o; o.x = dppf<CTRL>(v.x); o.y = dppf<CTRL>(v.y); o.z = dppf<CTRL>(v.z); o.w = dppf<CTRL>(v.w); return o; }
;     __device__ __forceinline__ void operator()(const f32x4 (&acc)[2][2][4][2], const Unit& u, int wr, int wc, int fr, int fq) const {
;     ...
;         const f32x4 w0 = *(const f32x4*)(cw + ch), w1 = *(const f32x4*)(cw + 2048 + ch), w2 = *(const f32x4*)(cw + 4096 + ch), bb = *(const f32x4*)(cb + ch);
; #pragma unroll
;         for (int ai = 0; ai < 2; ++ai) {
;             const int slab = u.pm * 4 + ai * 2 + wr;
;             f32x4 vprev = {0.f, 0.f, 0.f, 0.f};
; #pragma unroll
;             for (int m = 0; m < 4; ++m) {
;                 const int row = row0 + ai * HALF + m * 16;
;                 const float rs = rsv[ai][m];
;                 const f32x4 b = acc[ai][0][m][0] * rs, c = acc[ai][0][m][1] * rs, uu = acc[ai][1][m][0] * rs, g = acc[ai][1][m][1] * rs;
;                 const f32x4 v = c * uu;
;                 f32x4 sg;
; #pragma unroll
;                 for (int e = 0; e < 4; ++e) sg[e] = b[e] * g[e] * __builtin_amdgcn_rcpf(1.f + __expf(-g[e]));
;                 const f32x4 a1 = rorv<0x121>(v), a2 = rorv<0x122>(v), q1 = rorv<0x121>(vprev), q2 = rorv<0x122>(vprev);
;                 const f32x4 p1 = (fr == 0) ? q1 : a1, p2 = (fr < 2) ? q2 : a2;
;                 const f32x4 y = sg * (bb + w0 * p2 + w1 * p1 + w2 * v);
;                 u2 wy; wy.x = cvt_pk_bf16(y[0], y[1]); wy.y = cvt_pk_bf16(y[2], y[3]);
;                 u2 wv; wv.x = cvt_pk_bf16(v[0], v[1]); wv.y = cvt_pk_bf16(v[2], v[3]);
;                 if (m == 0) {
;                     if (fr >= 2) *(u2*)(Y + (size_t)row * 2048 + ch) = wy;
;                     else { u2 ws; ws.x = cvt_pk_bf16(sg[0], sg[1]); ws.y = cvt_pk_bf16(sg[2], sg[3]);
;                            *(u2*)(VB + ((size_t)slab * 4 + 2 + fr) * 2048 + ch) = wv; *(u2*)(BGB + ((size_t)slab * 2 + fr) * 2048 + ch) = ws; }
.LBB0_148:
	v_lshl_or_b32 v160, s42, 6, v169
	v_ashrrev_i32_e32 v161, 31, v160
	v_readlane_b32 s36, v254, 35
	v_lshlrev_b64 v[112:113], 2, v[160:161]
	v_readlane_b32 s42, v254, 41
	v_readlane_b32 s43, v254, 42
	v_readlane_b32 s44, v254, 43
	v_readlane_b32 s45, v254, 44
	v_lshl_add_u64 v[96:97], s[42:43], 0, v[112:113]
	v_lshl_add_u64 v[100:101], s[18:19], 0, v[112:113]
	v_lshl_add_u64 v[104:105], s[20:21], 0, v[112:113]
	v_lshl_add_u64 v[112:113], s[44:45], 0, v[112:113]
	global_load_dwordx4 v[96:99], v[96:97], off
	s_waitcnt vmcnt(0)
	v_pk_mul_f32 v[136:137], v[136:137], v[180:181] op_sel_hi:[1,0]
	global_load_dwordx4 v[100:103], v[100:101], off
	v_pk_mul_f32 v[140:141], v[140:141], v[180:181] op_sel_hi:[1,0]
	global_load_dwordx4 v[104:107], v[104:105], off
	v_mul_f32_e32 v179, 0xbfb8aa3b, v136
	global_load_dwordx4 v[112:115], v[112:113], off
	v_pk_mul_f32 v[140:141], v[140:141], v[136:137]
	v_mul_f32_e32 v136, 0xbfb8aa3b, v137
	v_exp_f32_e32 v179, v179
	v_exp_f32_e32 v136, v136
	v_pk_mul_f32 v[138:139], v[138:139], v[180:181] op_sel_hi:[1,0]
	v_pk_mul_f32 v[142:143], v[142:143], v[180:181] op_sel_hi:[1,0]
	v_add_f32_e32 v179, 1.0, v179
	v_add_f32_e32 v136, 1.0, v136
	v_rcp_f32_e32 v182, v179
	v_rcp_f32_e32 v183, v136
	v_pk_mul_f32 v[142:143], v[142:143], v[138:139]
	s_lshl_b32 s8, s34, 2
	v_pk_mul_f32 v[134:135], v[134:135], v[180:181] op_sel_hi:[1,0]
	v_pk_mul_f32 v[136:137], v[140:141], v[182:183]
	v_mul_f32_e32 v140, 0xbfb8aa3b, v138
	v_mul_f32_e32 v138, 0xbfb8aa3b, v139
	v_exp_f32_e32 v140, v140
	v_exp_f32_e32 v138, v138
	v_pk_mul_f32 v[130:131], v[130:131], v[180:181] op_sel_hi:[1,0]
	v_pk_mul_f32 v[128:129], v[128:129], v[180:181] op_sel_hi:[1,0]
	v_add_f32_e32 v140, 1.0, v140
	v_add_f32_e32 v138, 1.0, v138
	v_rcp_f32_e32 v140, v140
	v_rcp_f32_e32 v141, v138
	s_add_i32 s8, s8, s72
	s_ashr_i32 s9, s8, 31
	s_lshl_b64 s[34:35], s[8:9], 14
	v_pk_mul_f32 v[138:139], v[142:143], v[140:141]
	v_pk_mul_f32 v[140:141], v[132:133], v[180:181] op_sel_hi:[1,0]
	v_pk_mul_f32 v[132:133], v[134:135], v[130:131]
	v_pk_mul_f32 v[130:131], v[140:141], v[128:129]
	s_nop 1
	v_mov_b32_dpp v128, v130 row_ror:1 row_mask:0xf bank_mask:0xf
	v_mov_b32_dpp v129, v131 row_ror:1 row_mask:0xf bank_mask:0xf
	v_mov_b32_dpp v140, v132 row_ror:1 row_mask:0xf bank_mask:0xf
	v_mov_b32_dpp v141, v133 row_ror:1 row_mask:0xf bank_mask:0xf
	v_mov_b32_dpp v142, v130 row_ror:2 row_mask:0xf bank_mask:0xf
	v_mov_b32_dpp v143, v131 row_ror:2 row_mask:0xf bank_mask:0xf
	v_mov_b32_dpp v182, v132 row_ror:2 row_mask:0xf bank_mask:0xf
	v_mov_b32_dpp v183, v133 row_ror:2 row_mask:0xf bank_mask:0xf
	v_readlane_b32 s37, v254, 36
	v_readlane_b32 s38, v254, 37
	v_readlane_b32 s39, v254, 38
	v_readlane_b32 s40, v254, 39
	v_readlane_b32 s41, v254, 40
	v_readlane_b32 s46, v254, 45
	v_readlane_b32 s47, v254, 46
	v_readlane_b32 s48, v254, 47
	v_readlane_b32 s49, v254, 48
	v_readlane_b32 s50, v254, 49
	v_readlane_b32 s51, v254, 50
	s_and_saveexec_b64 s[42:43], s[4:5]
	s_xor_b64 s[42:43], exec, s[42:43]
	s_cbranch_execz .LBB0_150
	v_cvt_pk_bf16_f32 v134, v136, v137
	v_lshl_add_u64 v[136:137], v[148:149], 0, s[34:35]
	v_lshl_add_u64 v[136:137], v[160:161], 1, v[136:137]
	v_add_co_u32_e32 v136, vcc, 0x2000, v136
	v_cvt_pk_bf16_f32 v128, v130, v131
	v_cvt_pk_bf16_f32 v129, v132, v133
	s_lshl_b64 s[44:45], s[8:9], 13
	v_addc_co_u32_e32 v137, vcc, 0, v137, vcc
	v_cvt_pk_bf16_f32 v135, v138, v139
	global_store_dwordx2 v[136:137], v[128:129], off
	v_lshl_add_u64 v[180:181], v[150:151], 0, s[44:45]

; __device__ __forceinline__ unsigned cvt_pk_bf16(float lo, float hi) { f32x2 v = {lo, hi}; return __builtin_bit_cast(unsigned, __builtin_convertvector(v, bf2_t)); }
;     template <int CTRL> static __device__ __forceinline__ f32x4 rorv(const f32x4 v) { f32x4 o; o.x = dppf<CTRL>(v.x); o.y = dppf<CTRL>(v.y); o.z = dppf<CTRL>(v.z); o.w = dppf<CTRL>(v.w); return o; }
;     __device__ __forceinline__ void operator()(const f32x4 (&acc)[2][2][4][2], const Unit& u, int wr, int wc, int fr, int fq) const {
;     ...
;             for (int m = 0; m < 4; ++m) {
;                 const int row = row0 + ai * HALF + m * 16;
;                 const float rs = rsv[ai][m];
;                 const f32x4 b = acc[ai][0][m][0] * rs, c = acc[ai][0][m][1] * rs, uu = acc[ai][1][m][0] * rs, g = acc[ai][1][m][1] * rs;
;                 const f32x4 v = c * uu;
;                 f32x4 sg;
; #pragma unroll
;                 for (int e = 0; e < 4; ++e) sg[e] = b[e] * g[e] * __builtin_amdgcn_rcpf(1.f + __expf(-g[e]));
;                 const f32x4 a1 = rorv<0x121>(v), a2 = rorv<0x122>(v), q1 = rorv<0x121>(vprev), q2 = rorv<0x122>(vprev);
;                 const f32x4 p1 = (fr == 0) ? q1 : a1, p2 = (fr < 2) ? q2 : a2;
;                 const f32x4 y = sg * (bb + w0 * p2 + w1 * p1 + w2 * v);
;                 u2 wy; wy.x = cvt_pk_bf16(y[0], y[1]); wy.y = cvt_pk_bf16(y[2], y[3]);
;                 u2 wv; wv.x = cvt_pk_bf16(v[0], v[1]); wv.y = cvt_pk_bf16(v[2], v[3]);
;                 if (m == 0) {
;                     if (fr >= 2) *(u2*)(Y + (size_t)row * 2048 + ch) = wy;
;                     else { u2 ws; ws.x = cvt_pk_bf16(sg[0], sg[1]); ws.y = cvt_pk_bf16(sg[2], sg[3]);
;                            *(u2*)(VB + ((size_t)slab * 4 + 2 + fr) * 2048 + ch) = wv; *(u2*)(BGB + ((size_t)slab * 2 + fr) * 2048 + ch) = ws; }
;                 } else {
;                     *(u2*)(Y + (size_t)row * 2048 + ch) = wy;
;                     if (m == 3 && fr >= 14) *(u2*)(VB + ((size_t)slab * 4 + (fr - 14)) * 2048 + ch) = wv;
;                 }
.LBB0_152:
	s_or_b64 exec, exec, s[42:43]
	v_pk_mul_f32 v[126:127], v[126:127], v[178:179] op_sel_hi:[1,0]
	v_pk_mul_f32 v[124:125], v[124:125], v[178:179] op_sel_hi:[1,0]
	v_pk_mul_f32 v[122:123], v[122:123], v[178:179] op_sel_hi:[1,0]
	v_pk_mul_f32 v[120:121], v[120:121], v[178:179] op_sel_hi:[1,0]
	v_pk_mul_f32 v[122:123], v[126:127], v[122:123]
	v_pk_mul_f32 v[120:121], v[124:125], v[120:121]
	v_mov_b32_dpp v179, v132 row_ror:1 row_mask:0xf bank_mask:0xf
	v_pk_mul_f32 v[108:109], v[108:109], v[178:179] op_sel_hi:[1,0]
	v_pk_mul_f32 v[110:111], v[110:111], v[178:179] op_sel_hi:[1,0]
	v_mul_f32_e32 v124, 0xbfb8aa3b, v108
	v_mul_f32_e32 v125, 0xbfb8aa3b, v109
	v_mul_f32_e32 v126, 0xbfb8aa3b, v110
	v_mul_f32_e32 v127, 0xbfb8aa3b, v111
	v_exp_f32_e32 v124, v124
	v_exp_f32_e32 v125, v125
	v_exp_f32_e32 v126, v126
	v_exp_f32_e32 v127, v127
	v_add_f32_e32 v124, 1.0, v124
	v_add_f32_e32 v125, 1.0, v125
	v_add_f32_e32 v126, 1.0, v126
	v_add_f32_e32 v127, 1.0, v127
	v_rcp_f32_e32 v124, v124
	v_rcp_f32_e32 v125, v125
	v_rcp_f32_e32 v126, v126
	v_rcp_f32_e32 v127, v127
	v_lshlrev_b64 v[128:129], 1, v[160:161]
	v_lshl_add_u64 v[136:137], v[180:181], 0, v[128:129]
	v_pk_mul_f32 v[118:119], v[118:119], v[178:179] op_sel_hi:[1,0]
	v_pk_mul_f32 v[116:117], v[116:117], v[178:179] op_sel_hi:[1,0]
	global_store_dwordx2 v[136:137], v[134:135], off
	v_mov_b32_dpp v138, v120 row_ror:2 row_mask:0xf bank_mask:0xf
	v_mov_b32_dpp v139, v121 row_ror:2 row_mask:0xf bank_mask:0xf
	v_mov_b32_dpp v140, v122 row_ror:2 row_mask:0xf bank_mask:0xf
	v_mov_b32_dpp v141, v123 row_ror:2 row_mask:0xf bank_mask:0xf
	v_mov_b32_e32 v142, v130
	v_mov_b32_e32 v143, v131
	v_mov_b32_e32 v180, v133
	v_mov_b32_dpp v130, v130 row_ror:2 row_mask:0xf bank_mask:0xf
	v_mov_b32_dpp v131, v131 row_ror:2 row_mask:0xf bank_mask:0xf
	v_mov_b32_dpp v132, v132 row_ror:2 row_mask:0xf bank_mask:0xf
	v_mov_b32_dpp v133, v133 row_ror:2 row_mask:0xf bank_mask:0xf
	v_pk_mul_f32 v[110:111], v[118:119], v[110:111]
	v_pk_mul_f32 v[108:109], v[116:117], v[108:109]
	v_mov_b32_dpp v134, v120 row_ror:1 row_mask:0xf bank_mask:0xf
	v_mov_b32_dpp v135, v121 row_ror:1 row_mask:0xf bank_mask:0xf
	v_mov_b32_dpp v136, v122 row_ror:1 row_mask:0xf bank_mask:0xf
	v_mov_b32_dpp v137, v123 row_ror:1 row_mask:0xf bank_mask:0xf
	v_mov_b32_dpp v142, v142 row_ror:1 row_mask:0xf bank_mask:0xf
	v_mov_b32_dpp v143, v143 row_ror:1 row_mask:0xf bank_mask:0xf
	v_mov_b32_dpp v180, v180 row_ror:1 row_mask:0xf bank_mask:0xf
	v_pk_mul_f32 v[110:111], v[110:111], v[126:127]
	v_pk_mul_f32 v[108:109], v[108:109], v[124:125]
	v_cndmask_b32_e64 v125, v141, v133, s[4:5]
	v_cndmask_b32_e64 v124, v140, v132, s[4:5]
	v_cndmask_b32_e64 v127, v139, v131, s[4:5]
	v_cndmask_b32_e64 v126, v138, v130, s[4:5]
	v_pk_mul_f32 v[94:95], v[94:95], v[176:177] op_sel_hi:[1,0]
	v_pk_mul_f32 v[92:93], v[92:93], v[176:177] op_sel_hi:[1,0]
	v_pk_mul_f32 v[90:91], v[90:91], v[176:177] op_sel_hi:[1,0]
	v_pk_mul_f32 v[88:89], v[88:89], v[176:177] op_sel_hi:[1,0]
	v_pk_mul_f32 v[80:81], v[80:81], v[176:177] op_sel_hi:[1,0]
	v_pk_mul_f32 v[82:83], v[82:83], v[176:177] op_sel_hi:[1,0]
	v_cndmask_b32_e64 v117, v137, v180, s[2:3]
	v_cndmask_b32_e64 v116, v136, v179, s[2:3]
	v_cndmask_b32_e64 v119, v135, v143, s[2:3]
	v_cndmask_b32_e64 v118, v134, v142, s[2:3]
	s_waitcnt vmcnt(1)
	v_pk_fma_f32 v[124:125], v[98:99], v[124:125], v[114:115]
	v_pk_fma_f32 v[126:127], v[96:97], v[126:127], v[112:113]
	v_pk_mul_f32 v[90:91], v[90:91], v[94:95]
	v_pk_mul_f32 v[88:89], v[88:89], v[92:93]
	v_mul_f32_e32 v92, 0xbfb8aa3b, v80
	v_mul_f32_e32 v93, 0xbfb8aa3b, v81
	v_mul_f32_e32 v94, 0xbfb8aa3b, v82
	v_mul_f32_e32 v95, 0xbfb8aa3b, v83
	v_pk_fma_f32 v[116:117], v[102:103], v[116:117], v[124:125]
	v_pk_fma_f32 v[118:119], v[100:101], v[118:119], v[126:127]
	v_exp_f32_e32 v92, v92
	v_exp_f32_e32 v93, v93
	v_exp_f32_e32 v94, v94
	v_exp_f32_e32 v95, v95
	v_pk_fma_f32 v[116:117], v[122:123], v[106:107], v[116:117]
	v_pk_fma_f32 v[118:119], v[120:121], v[104:105], v[118:119]
	v_pk_mul_f32 v[110:111], v[110:111], v[116:117]
	v_pk_mul_f32 v[108:109], v[108:109], v[118:119]
	v_add_f32_e32 v92, 1.0, v92
	v_cvt_pk_bf16_f32 v108, v108, v109
	v_cvt_pk_bf16_f32 v109, v110, v111
	v_or_b32_e32 v110, 16, v164
	v_ashrrev_i32_e32 v111, 31, v110
	v_add_f32_e32 v93, 1.0, v93
	v_add_f32_e32 v94, 1.0, v94
	v_add_f32_e32 v95, 1.0, v95
	v_lshlrev_b64 v[110:111], 12, v[110:111]
	v_rcp_f32_e32 v92, v92
	v_rcp_f32_e32 v93, v93
	v_rcp_f32_e32 v94, v94
	v_rcp_f32_e32 v95, v95
	v_lshl_add_u64 v[110:111], s[60:61], 0, v[110:111]
	v_lshl_add_u64 v[110:111], v[110:111], 0, v[128:129]
	v_pk_mul_f32 v[86:87], v[86:87], v[176:177] op_sel_hi:[1,0]
	v_pk_mul_f32 v[84:85], v[84:85], v[176:177] op_sel_hi:[1,0]
	global_store_dwordx2 v[110:111], v[108:109], off
	v_mov_b32_dpp v116, v88 row_ror:2 row_mask:0xf bank_mask:0xf
	v_mov_b32_dpp v117, v89 row_ror:2 row_mask:0xf bank_mask:0xf
	v_mov_b32_dpp v118, v90 row_ror:2 row_mask:0xf bank_mask:0xf
	v_mov_b32_dpp v119, v91 row_ror:2 row_mask:0xf bank_mask:0xf
	v_pk_mul_f32 v[82:83], v[86:87], v[82:83]
	v_pk_mul_f32 v[80:81], v[84:85], v[80:81]
	v_mov_b32_dpp v108, v88 row_ror:1 row_mask:0xf bank_mask:0xf
	v_mov_b32_dpp v109, v89 row_ror:1 row_mask:0xf bank_mask:0xf
	v_mov_b32_dpp v110, v90 row_ror:1 row_mask:0xf bank_mask:0xf
	v_mov_b32_dpp v111, v91 row_ror:1 row_mask:0xf bank_mask:0xf
	v_pk_mul_f32 v[82:83], v[82:83], v[94:95]
	v_pk_mul_f32 v[80:81], v[80:81], v[92:93]
	v_cndmask_b32_e64 v93, v119, v141, s[4:5]
	v_cndmask_b32_e64 v92, v118, v140, s[4:5]
	v_cndmask_b32_e64 v95, v117, v139, s[4:5]
	v_cndmask_b32_e64 v94, v116, v138, s[4:5]
	v_cndmask_b32_e64 v85, v111, v137, s[2:3]
; __device__ __forceinline__ unsigned cvt_pk_bf16(float lo, float hi) { f32x2 v = {lo, hi}; return __builtin_bit_cast(unsigned, __builtin_convertvector(v, bf2_t)); }
;     template <int CTRL> static __device__ __forceinline__ f32x4 rorv(const f32x4 v) { f32x4 o; o.x = dppf<CTRL>(v.x); o.y = dppf<CTRL>(v.y); o.z = dppf<CTRL>(v.z); o.w = dppf<CTRL>(v.w); return o; }
;     __device__ __forceinline__ void operator()(const f32x4 (&acc)[2][2][4][2], const Unit& u, int wr, int wc, int fr, int fq) const {
;     ...
;             for (int m = 0; m < 4; ++m) {
;                 const int row = row0 + ai * HALF + m * 16;
;                 const float rs = rsv[ai][m];
;                 const f32x4 b = acc[ai][0][m][0] * rs, c = acc[ai][0][m][1] * rs, uu = acc[ai][1][m][0] * rs, g = acc[ai][1][m][1] * rs;
;                 const f32x4 v = c * uu;
;                 f32x4 sg;
; #pragma unroll
;                 for (int e = 0; e < 4; ++e) sg[e] = b[e] * g[e] * __builtin_amdgcn_rcpf(1.f + __expf(-g[e]));
;                 const f32x4 a1 = rorv<0x121>(v), a2 = rorv<0x122>(v), q1 = rorv<0x121>(vprev), q2 = rorv<0x122>(vprev);
;                 const f32x4 p1 = (fr == 0) ? q1 : a1, p2 = (fr < 2) ? q2 : a2;
;                 const f32x4 y = sg * (bb + w0 * p2 + w1 * p1 + w2 * v);
;                 u2 wy; wy.x = cvt_pk_bf16(y[0], y[1]); wy.y = cvt_pk_bf16(y[2], y[3]);
;                 u2 wv; wv.x = cvt_pk_bf16(v[0], v[1]); wv.y = cvt_pk_bf16(v[2], v[3]);
;                 if (m == 0) {
;                     if (fr >= 2) *(u2*)(Y + (size_t)row * 2048 + ch) = wy;
;                     else { u2 ws; ws.x = cvt_pk_bf16(sg[0], sg[1]); ws.y = cvt_pk_bf16(sg[2], sg[3]);
;                            *(u2*)(VB + ((size_t)slab * 4 + 2 + fr) * 2048 + ch) = wv; *(u2*)(BGB + ((size_t)slab * 2 + fr) * 2048 + ch) = ws; }
;                 } else {
;                     *(u2*)(Y + (size_t)row * 2048 + ch) = wy;
;                     if (m == 3 && fr >= 14) *(u2*)(VB + ((size_t)slab * 4 + (fr - 14)) * 2048 + ch) = wv;
;                 }
	v_cndmask_b32_e64 v84, v110, v136, s[2:3]
	v_cndmask_b32_e64 v87, v109, v135, s[2:3]
	v_cndmask_b32_e64 v86, v108, v134, s[2:3]
	v_pk_fma_f32 v[92:93], v[98:99], v[92:93], v[114:115]
	v_pk_fma_f32 v[94:95], v[96:97], v[94:95], v[112:113]
	v_pk_fma_f32 v[84:85], v[102:103], v[84:85], v[92:93]
	v_pk_fma_f32 v[86:87], v[100:101], v[86:87], v[94:95]
	v_pk_fma_f32 v[84:85], v[90:91], v[106:107], v[84:85]
	v_pk_fma_f32 v[86:87], v[88:89], v[104:105], v[86:87]
	v_pk_mul_f32 v[82:83], v[82:83], v[84:85]
	v_pk_mul_f32 v[80:81], v[80:81], v[86:87]
	v_pk_mul_f32 v[78:79], v[78:79], v[174:175] op_sel_hi:[1,0]
	v_cvt_pk_bf16_f32 v80, v80, v81
	v_cvt_pk_bf16_f32 v81, v82, v83
	v_or_b32_e32 v82, 32, v164
	v_ashrrev_i32_e32 v83, 31, v82
	v_lshlrev_b64 v[82:83], 12, v[82:83]
	v_lshl_add_u64 v[82:83], s[60:61], 0, v[82:83]
	v_lshl_add_u64 v[82:83], v[82:83], 0, v[128:129]
	global_store_dwordx2 v[82:83], v[80:81], off
	v_pk_mul_f32 v[76:77], v[76:77], v[174:175] op_sel_hi:[1,0]
	v_pk_mul_f32 v[74:75], v[74:75], v[174:175] op_sel_hi:[1,0]
	v_pk_mul_f32 v[80:81], v[72:73], v[174:175] op_sel_hi:[1,0]
	v_pk_mul_f32 v[64:65], v[64:65], v[174:175] op_sel_hi:[1,0]
	v_pk_mul_f32 v[66:67], v[66:67], v[174:175] op_sel_hi:[1,0]
	v_pk_mul_f32 v[72:73], v[74:75], v[78:79]
	v_pk_mul_f32 v[74:75], v[80:81], v[76:77]
	v_mul_f32_e32 v76, 0xbfb8aa3b, v64
	v_mul_f32_e32 v77, 0xbfb8aa3b, v65
	v_mul_f32_e32 v78, 0xbfb8aa3b, v66
	v_mul_f32_e32 v79, 0xbfb8aa3b, v67
	v_exp_f32_e32 v76, v76
	v_exp_f32_e32 v77, v77
	v_exp_f32_e32 v78, v78
	v_exp_f32_e32 v79, v79
	v_add_f32_e32 v76, 1.0, v76
	v_add_f32_e32 v77, 1.0, v77
	v_add_f32_e32 v78, 1.0, v78
	v_add_f32_e32 v79, 1.0, v79
	v_rcp_f32_e32 v76, v76
	v_rcp_f32_e32 v77, v77
	v_rcp_f32_e32 v78, v78
	v_rcp_f32_e32 v79, v79
	v_pk_mul_f32 v[70:71], v[70:71], v[174:175] op_sel_hi:[1,0]
	v_pk_mul_f32 v[68:69], v[68:69], v[174:175] op_sel_hi:[1,0]
	v_mov_b32_dpp v84, v74 row_ror:2 row_mask:0xf bank_mask:0xf
	v_mov_b32_dpp v85, v75 row_ror:2 row_mask:0xf bank_mask:0xf
	v_mov_b32_dpp v86, v72 row_ror:2 row_mask:0xf bank_mask:0xf
	v_mov_b32_dpp v87, v73 row_ror:2 row_mask:0xf bank_mask:0xf
	v_pk_mul_f32 v[66:67], v[70:71], v[66:67]
	v_pk_mul_f32 v[64:65], v[68:69], v[64:65]
	v_mov_b32_dpp v80, v74 row_ror:1 row_mask:0xf bank_mask:0xf
	v_mov_b32_dpp v81, v75 row_ror:1 row_mask:0xf bank_mask:0xf
	v_mov_b32_dpp v82, v72 row_ror:1 row_mask:0xf bank_mask:0xf
	v_mov_b32_dpp v83, v73 row_ror:1 row_mask:0xf bank_mask:0xf
	v_pk_mul_f32 v[66:67], v[66:67], v[78:79]
	v_pk_mul_f32 v[64:65], v[64:65], v[76:77]
	v_cndmask_b32_e64 v77, v87, v119, s[4:5]
	v_cndmask_b32_e64 v76, v86, v118, s[4:5]
	v_cndmask_b32_e64 v79, v85, v117, s[4:5]
	v_cndmask_b32_e64 v78, v84, v116, s[4:5]
	v_cndmask_b32_e64 v69, v83, v111, s[2:3]
	v_cndmask_b32_e64 v68, v82, v110, s[2:3]
	v_cndmask_b32_e64 v71, v81, v109, s[2:3]
	v_cndmask_b32_e64 v70, v80, v108, s[2:3]
	v_pk_fma_f32 v[76:77], v[98:99], v[76:77], v[114:115]
	v_pk_fma_f32 v[78:79], v[96:97], v[78:79], v[112:113]
	v_pk_fma_f32 v[68:69], v[102:103], v[68:69], v[76:77]
	v_pk_fma_f32 v[70:71], v[100:101], v[70:71], v[78:79]
	v_pk_fma_f32 v[68:69], v[72:73], v[106:107], v[68:69]
	v_pk_fma_f32 v[70:71], v[74:75], v[104:105], v[70:71]
	v_pk_mul_f32 v[66:67], v[66:67], v[68:69]
	v_pk_mul_f32 v[64:65], v[64:65], v[70:71]
	s_nop 0
	v_cvt_pk_bf16_f32 v64, v64, v65
	v_cvt_pk_bf16_f32 v65, v66, v67
	v_or_b32_e32 v66, 48, v164
	v_ashrrev_i32_e32 v67, 31, v66
	v_lshlrev_b64 v[66:67], 12, v[66:67]
	v_lshl_add_u64 v[66:67], s[60:61], 0, v[66:67]
	v_lshl_add_u64 v[66:67], v[66:67], 0, v[128:129]
	global_store_dwordx2 v[66:67], v[64:65], off
	s_and_saveexec_b64 s[42:43], s[6:7]
	s_cbranch_execz .LBB0_154
	v_lshl_add_u64 v[66:67], v[152:153], 0, s[34:35]
	v_cvt_pk_bf16_f32 v64, v74, v75
	v_cvt_pk_bf16_f32 v65, v72, v73
	v_lshl_add_u64 v[66:67], v[160:161], 1, v[66:67]
	global_store_dwordx2 v[66:67], v[64:65], off
.LBB0_154:
	s_or_b64 exec, exec, s[42:43]
	v_pk_mul_f32 v[56:57], v[56:57], v[172:173] op_sel_hi:[1,0]
	v_pk_mul_f32 v[60:61], v[60:61], v[172:173] op_sel_hi:[1,0]
	v_mul_f32_e32 v64, 0xbfb8aa3b, v56
	v_pk_mul_f32 v[60:61], v[60:61], v[56:57]
	v_mul_f32_e32 v56, 0xbfb8aa3b, v57
	v_exp_f32_e32 v64, v64
	v_exp_f32_e32 v56, v56
	v_pk_mul_f32 v[58:59], v[58:59], v[172:173] op_sel_hi:[1,0]
	v_pk_mul_f32 v[62:63], v[62:63], v[172:173] op_sel_hi:[1,0]
	v_add_f32_e32 v64, 1.0, v64
	v_add_f32_e32 v56, 1.0, v56
	v_rcp_f32_e32 v64, v64
	v_rcp_f32_e32 v65, v56
	v_pk_mul_f32 v[62:63], v[62:63], v[58:59]
	v_pk_mul_f32 v[54:55], v[54:55], v[172:173] op_sel_hi:[1,0]
	v_pk_mul_f32 v[52:53], v[52:53], v[172:173] op_sel_hi:[1,0]
	v_pk_mul_f32 v[56:57], v[60:61], v[64:65]
	v_mul_f32_e32 v60, 0xbfb8aa3b, v58
	v_mul_f32_e32 v58, 0xbfb8aa3b, v59
	v_exp_f32_e32 v60, v60
	v_exp_f32_e32 v58, v58
	v_pk_mul_f32 v[50:51], v[50:51], v[172:173] op_sel_hi:[1,0]
	v_pk_mul_f32 v[48:49], v[48:49], v[172:173] op_sel_hi:[1,0]
	v_add_f32_e32 v60, 1.0, v60
	v_add_f32_e32 v58, 1.0, v58
	v_rcp_f32_e32 v60, v60
	v_rcp_f32_e32 v61, v58
	s_add_i32 s34, s8, 2
	v_pk_mul_f32 v[50:51], v[54:55], v[50:51]
	v_pk_mul_f32 v[48:49], v[52:53], v[48:49]
	s_ashr_i32 s35, s34, 31
	v_pk_mul_f32 v[58:59], v[62:63], v[60:61]
	s_lshl_b64 s[8:9], s[34:35], 14
	v_mov_b32_dpp v54, v48 row_ror:1 row_mask:0xf bank_mask:0xf
	v_mov_b32_dpp v55, v49 row_ror:1 row_mask:0xf bank_mask:0xf
	v_mov_b32_dpp v60, v50 row_ror:1 row_mask:0xf bank_mask:0xf
	v_mov_b32_dpp v61, v51 row_ror:1 row_mask:0xf bank_mask:0xf
	v_mov_b32_dpp v62, v48 row_ror:2 row_mask:0xf bank_mask:0xf
	v_mov_b32_dpp v63, v49 row_ror:2 row_mask:0xf bank_mask:0xf
	v_mov_b32_dpp v66, v50 row_ror:2 row_mask:0xf bank_mask:0xf
	v_mov_b32_dpp v67, v51 row_ror:2 row_mask:0xf bank_mask:0xf
	s_and_saveexec_b64 s[42:43], s[4:5]
	s_xor_b64 s[42:43], exec, s[42:43]
	s_cbranch_execz .LBB0_156
	v_cvt_pk_bf16_f32 v52, v56, v57
	v_lshl_add_u64 v[56:57], v[148:149], 0, s[8:9]
	v_lshl_add_u64 v[56:57], v[160:161], 1, v[56:57]
	s_lshl_b64 s[34:35], s[34:35], 13
	v_add_co_u32_e32 v56, vcc, 0x2000, v56
	v_cvt_pk_bf16_f32 v54, v48, v49
	v_cvt_pk_bf16_f32 v55, v50, v51
	v_cvt_pk_bf16_f32 v53, v58, v59
	v_addc_co_u32_e32 v57, vcc, 0, v57, vcc
	v_lshl_add_u64 v[64:65], v[150:151], 0, s[34:35]
	global_store_dwordx2 v[56:57], v[54:55], off

; __device__ __forceinline__ unsigned cvt_pk_bf16(float lo, float hi) { f32x2 v = {lo, hi}; return __builtin_bit_cast(unsigned, __builtin_convertvector(v, bf2_t)); }
;     template <int CTRL> static __device__ __forceinline__ f32x4 rorv(const f32x4 v) { f32x4 o; o.x = dppf<CTRL>(v.x); o.y = dppf<CTRL>(v.y); o.z = dppf<CTRL>(v.z); o.w = dppf<CTRL>(v.w); return o; }
;     __device__ __forceinline__ void operator()(const f32x4 (&acc)[2][2][4][2], const Unit& u, int wr, int wc, int fr, int fq) const {
;     ...
;             for (int m = 0; m < 4; ++m) {
;                 const int row = row0 + ai * HALF + m * 16;
;                 const float rs = rsv[ai][m];
;                 const f32x4 b = acc[ai][0][m][0] * rs, c = acc[ai][0][m][1] * rs, uu = acc[ai][1][m][0] * rs, g = acc[ai][1][m][1] * rs;
;                 const f32x4 v = c * uu;
;                 f32x4 sg;
; #pragma unroll
;                 for (int e = 0; e < 4; ++e) sg[e] = b[e] * g[e] * __builtin_amdgcn_rcpf(1.f + __expf(-g[e]));
;                 const f32x4 a1 = rorv<0x121>(v), a2 = rorv<0x122>(v), q1 = rorv<0x121>(vprev), q2 = rorv<0x122>(vprev);
;                 const f32x4 p1 = (fr == 0) ? q1 : a1, p2 = (fr < 2) ? q2 : a2;
;                 const f32x4 y = sg * (bb + w0 * p2 + w1 * p1 + w2 * v);
;                 u2 wy; wy.x = cvt_pk_bf16(y[0], y[1]); wy.y = cvt_pk_bf16(y[2], y[3]);
;                 u2 wv; wv.x = cvt_pk_bf16(v[0], v[1]); wv.y = cvt_pk_bf16(v[2], v[3]);
;                 if (m == 0) {
;                     if (fr >= 2) *(u2*)(Y + (size_t)row * 2048 + ch) = wy;
;                     else { u2 ws; ws.x = cvt_pk_bf16(sg[0], sg[1]); ws.y = cvt_pk_bf16(sg[2], sg[3]);
;                            *(u2*)(VB + ((size_t)slab * 4 + 2 + fr) * 2048 + ch) = wv; *(u2*)(BGB + ((size_t)slab * 2 + fr) * 2048 + ch) = ws; }
;                 } else {
;                     *(u2*)(Y + (size_t)row * 2048 + ch) = wy;
;                     if (m == 3 && fr >= 14) *(u2*)(VB + ((size_t)slab * 4 + (fr - 14)) * 2048 + ch) = wv;
;                 }
.LBB0_158:
	s_or_b64 exec, exec, s[34:35]
	v_pk_mul_f32 v[46:47], v[46:47], v[168:169] op_sel_hi:[1,0]
	v_pk_mul_f32 v[44:45], v[44:45], v[168:169] op_sel_hi:[1,0]
	v_pk_mul_f32 v[42:43], v[42:43], v[168:169] op_sel_hi:[1,0]
	v_pk_mul_f32 v[40:41], v[40:41], v[168:169] op_sel_hi:[1,0]
	v_pk_mul_f32 v[32:33], v[32:33], v[168:169] op_sel_hi:[1,0]
	v_pk_mul_f32 v[34:35], v[34:35], v[168:169] op_sel_hi:[1,0]
	v_pk_mul_f32 v[42:43], v[46:47], v[42:43]
	v_pk_mul_f32 v[40:41], v[44:45], v[40:41]
	v_mul_f32_e32 v44, 0xbfb8aa3b, v32
	v_mul_f32_e32 v45, 0xbfb8aa3b, v33
	v_mul_f32_e32 v46, 0xbfb8aa3b, v34
	v_mul_f32_e32 v47, 0xbfb8aa3b, v35
	v_exp_f32_e32 v44, v44
	v_exp_f32_e32 v45, v45
	v_exp_f32_e32 v46, v46
	v_exp_f32_e32 v47, v47
	v_add_f32_e32 v44, 1.0, v44
	v_add_f32_e32 v45, 1.0, v45
	v_add_f32_e32 v46, 1.0, v46
	v_add_f32_e32 v47, 1.0, v47
	v_rcp_f32_e32 v44, v44
	v_rcp_f32_e32 v45, v45
	v_rcp_f32_e32 v46, v46
	v_rcp_f32_e32 v47, v47
	v_lshl_add_u64 v[54:55], v[64:65], 0, v[128:129]
	v_pk_mul_f32 v[38:39], v[38:39], v[168:169] op_sel_hi:[1,0]
	v_pk_mul_f32 v[36:37], v[36:37], v[168:169] op_sel_hi:[1,0]
	global_store_dwordx2 v[54:55], v[52:53], off
	v_mov_b32_dpp v56, v40 row_ror:2 row_mask:0xf bank_mask:0xf
	v_mov_b32_dpp v57, v41 row_ror:2 row_mask:0xf bank_mask:0xf
	v_mov_b32_dpp v58, v42 row_ror:2 row_mask:0xf bank_mask:0xf
	v_mov_b32_dpp v59, v43 row_ror:2 row_mask:0xf bank_mask:0xf
	v_mov_b32_e32 v60, v48
	v_mov_b32_e32 v61, v49
	v_mov_b32_e32 v62, v50
	v_mov_b32_e32 v63, v51
	v_mov_b32_dpp v48, v48 row_ror:2 row_mask:0xf bank_mask:0xf
	v_mov_b32_dpp v49, v49 row_ror:2 row_mask:0xf bank_mask:0xf
	v_mov_b32_dpp v50, v50 row_ror:2 row_mask:0xf bank_mask:0xf
	v_mov_b32_dpp v51, v51 row_ror:2 row_mask:0xf bank_mask:0xf
	v_pk_mul_f32 v[34:35], v[38:39], v[34:35]
	v_pk_mul_f32 v[32:33], v[36:37], v[32:33]
	v_mov_b32_dpp v52, v40 row_ror:1 row_mask:0xf bank_mask:0xf
	v_mov_b32_dpp v53, v41 row_ror:1 row_mask:0xf bank_mask:0xf
	v_mov_b32_dpp v54, v42 row_ror:1 row_mask:0xf bank_mask:0xf
	v_mov_b32_dpp v55, v43 row_ror:1 row_mask:0xf bank_mask:0xf
	v_mov_b32_dpp v60, v60 row_ror:1 row_mask:0xf bank_mask:0xf
	v_mov_b32_dpp v61, v61 row_ror:1 row_mask:0xf bank_mask:0xf
	v_mov_b32_dpp v62, v62 row_ror:1 row_mask:0xf bank_mask:0xf
	v_mov_b32_dpp v63, v63 row_ror:1 row_mask:0xf bank_mask:0xf
	v_pk_mul_f32 v[34:35], v[34:35], v[46:47]
	v_pk_mul_f32 v[32:33], v[32:33], v[44:45]
	v_cndmask_b32_e64 v45, v59, v51, s[4:5]
	v_cndmask_b32_e64 v44, v58, v50, s[4:5]
	v_cndmask_b32_e64 v47, v57, v49, s[4:5]
	v_cndmask_b32_e64 v46, v56, v48, s[4:5]
	v_pk_mul_f32 v[30:31], v[30:31], v[166:167] op_sel_hi:[1,0]
	v_pk_mul_f32 v[28:29], v[28:29], v[166:167] op_sel_hi:[1,0]
	v_pk_mul_f32 v[26:27], v[26:27], v[166:167] op_sel_hi:[1,0]
	v_pk_mul_f32 v[24:25], v[24:25], v[166:167] op_sel_hi:[1,0]
	v_pk_mul_f32 v[16:17], v[16:17], v[166:167] op_sel_hi:[1,0]
	v_pk_mul_f32 v[18:19], v[18:19], v[166:167] op_sel_hi:[1,0]
	v_cndmask_b32_e64 v37, v55, v63, s[2:3]
	v_cndmask_b32_e64 v36, v54, v62, s[2:3]
	v_cndmask_b32_e64 v39, v53, v61, s[2:3]
	v_cndmask_b32_e64 v38, v52, v60, s[2:3]
	v_pk_fma_f32 v[44:45], v[98:99], v[44:45], v[114:115]
	v_pk_fma_f32 v[46:47], v[96:97], v[46:47], v[112:113]
	v_pk_mul_f32 v[26:27], v[26:27], v[30:31]
	v_pk_mul_f32 v[24:25], v[24:25], v[28:29]
	v_mul_f32_e32 v28, 0xbfb8aa3b, v16
	v_mul_f32_e32 v29, 0xbfb8aa3b, v17
	v_mul_f32_e32 v30, 0xbfb8aa3b, v18
	v_mul_f32_e32 v31, 0xbfb8aa3b, v19
	v_pk_fma_f32 v[36:37], v[102:103], v[36:37], v[44:45]
	v_pk_fma_f32 v[38:39], v[100:101], v[38:39], v[46:47]
	v_exp_f32_e32 v28, v28
	v_exp_f32_e32 v29, v29
	v_exp_f32_e32 v30, v30
	v_exp_f32_e32 v31, v31
	v_pk_fma_f32 v[36:37], v[42:43], v[106:107], v[36:37]
	v_pk_fma_f32 v[38:39], v[40:41], v[104:105], v[38:39]
	v_pk_mul_f32 v[34:35], v[34:35], v[36:37]
	v_pk_mul_f32 v[32:33], v[32:33], v[38:39]
	v_add_f32_e32 v28, 1.0, v28
	v_cvt_pk_bf16_f32 v32, v32, v33
	v_cvt_pk_bf16_f32 v33, v34, v35
	v_lshlrev_b64 v[34:35], 12, v[164:165]
	v_lshl_add_u64 v[34:35], s[60:61], 0, v[34:35]
	v_add_f32_e32 v29, 1.0, v29
	v_add_f32_e32 v30, 1.0, v30
	v_add_f32_e32 v31, 1.0, v31
	v_lshl_add_u64 v[34:35], v[34:35], 0, v[128:129]
	s_mov_b32 s23, 0x90000
	v_rcp_f32_e32 v28, v28
	v_rcp_f32_e32 v29, v29
	v_rcp_f32_e32 v30, v30
	v_rcp_f32_e32 v31, v31
	v_add_co_u32_e32 v36, vcc, s23, v34
	s_nop 0
	v_addc_co_u32_e32 v37, vcc, 0, v35, vcc
	v_pk_mul_f32 v[22:23], v[22:23], v[166:167] op_sel_hi:[1,0]
	v_pk_mul_f32 v[20:21], v[20:21], v[166:167] op_sel_hi:[1,0]
; __device__ __forceinline__ unsigned cvt_pk_bf16(float lo, float hi) { f32x2 v = {lo, hi}; return __builtin_bit_cast(unsigned, __builtin_convertvector(v, bf2_t)); }
;     template <int CTRL> static __device__ __forceinline__ f32x4 rorv(const f32x4 v) { f32x4 o; o.x = dppf<CTRL>(v.x); o.y = dppf<CTRL>(v.y); o.z = dppf<CTRL>(v.z); o.w = dppf<CTRL>(v.w); return o; }
;     __device__ __forceinline__ void operator()(const f32x4 (&acc)[2][2][4][2], const Unit& u, int wr, int wc, int fr, int fq) const {
;     ...
;             for (int m = 0; m < 4; ++m) {
;                 const int row = row0 + ai * HALF + m * 16;
;                 const float rs = rsv[ai][m];
;                 const f32x4 b = acc[ai][0][m][0] * rs, c = acc[ai][0][m][1] * rs, uu = acc[ai][1][m][0] * rs, g = acc[ai][1][m][1] * rs;
;                 const f32x4 v = c * uu;
;                 f32x4 sg;
; #pragma unroll
;                 for (int e = 0; e < 4; ++e) sg[e] = b[e] * g[e] * __builtin_amdgcn_rcpf(1.f + __expf(-g[e]));
;                 const f32x4 a1 = rorv<0x121>(v), a2 = rorv<0x122>(v), q1 = rorv<0x121>(vprev), q2 = rorv<0x122>(vprev);
;                 const f32x4 p1 = (fr == 0) ? q1 : a1, p2 = (fr < 2) ? q2 : a2;
;                 const f32x4 y = sg * (bb + w0 * p2 + w1 * p1 + w2 * v);
;                 u2 wy; wy.x = cvt_pk_bf16(y[0], y[1]); wy.y = cvt_pk_bf16(y[2], y[3]);
;                 u2 wv; wv.x = cvt_pk_bf16(v[0], v[1]); wv.y = cvt_pk_bf16(v[2], v[3]);
;                 if (m == 0) {
;                     if (fr >= 2) *(u2*)(Y + (size_t)row * 2048 + ch) = wy;
;                     else { u2 ws; ws.x = cvt_pk_bf16(sg[0], sg[1]); ws.y = cvt_pk_bf16(sg[2], sg[3]);
;                            *(u2*)(VB + ((size_t)slab * 4 + 2 + fr) * 2048 + ch) = wv; *(u2*)(BGB + ((size_t)slab * 2 + fr) * 2048 + ch) = ws; }
;                 } else {
;                     *(u2*)(Y + (size_t)row * 2048 + ch) = wy;
;                     if (m == 3 && fr >= 14) *(u2*)(VB + ((size_t)slab * 4 + (fr - 14)) * 2048 + ch) = wv;
;                 }
	global_store_dwordx2 v[36:37], v[32:33], off
	v_mov_b32_dpp v38, v24 row_ror:2 row_mask:0xf bank_mask:0xf
	v_mov_b32_dpp v39, v25 row_ror:2 row_mask:0xf bank_mask:0xf
	v_mov_b32_dpp v40, v26 row_ror:2 row_mask:0xf bank_mask:0xf
	v_mov_b32_dpp v41, v27 row_ror:2 row_mask:0xf bank_mask:0xf
	v_pk_mul_f32 v[18:19], v[22:23], v[18:19]
	v_pk_mul_f32 v[16:17], v[20:21], v[16:17]
	v_mov_b32_dpp v32, v24 row_ror:1 row_mask:0xf bank_mask:0xf
	v_mov_b32_dpp v33, v25 row_ror:1 row_mask:0xf bank_mask:0xf
	v_mov_b32_dpp v36, v26 row_ror:1 row_mask:0xf bank_mask:0xf
	v_mov_b32_dpp v37, v27 row_ror:1 row_mask:0xf bank_mask:0xf
	v_pk_mul_f32 v[18:19], v[18:19], v[30:31]
	v_pk_mul_f32 v[16:17], v[16:17], v[28:29]
	v_cndmask_b32_e64 v29, v41, v59, s[4:5]
	v_cndmask_b32_e64 v28, v40, v58, s[4:5]
	v_cndmask_b32_e64 v31, v39, v57, s[4:5]
	v_cndmask_b32_e64 v30, v38, v56, s[4:5]
	v_cndmask_b32_e64 v21, v37, v55, s[2:3]
	v_cndmask_b32_e64 v20, v36, v54, s[2:3]
	v_cndmask_b32_e64 v23, v33, v53, s[2:3]
	v_cndmask_b32_e64 v22, v32, v52, s[2:3]
	v_pk_fma_f32 v[28:29], v[98:99], v[28:29], v[114:115]
	v_pk_fma_f32 v[30:31], v[96:97], v[30:31], v[112:113]
	v_pk_fma_f32 v[20:21], v[102:103], v[20:21], v[28:29]
	v_pk_fma_f32 v[22:23], v[100:101], v[22:23], v[30:31]
	v_pk_fma_f32 v[20:21], v[26:27], v[106:107], v[20:21]
	v_pk_fma_f32 v[22:23], v[24:25], v[104:105], v[22:23]
	v_pk_mul_f32 v[18:19], v[18:19], v[20:21]
	v_pk_mul_f32 v[16:17], v[16:17], v[22:23]
	s_mov_b32 s23, 0xa0000
	v_cvt_pk_bf16_f32 v16, v16, v17
	v_cvt_pk_bf16_f32 v17, v18, v19
	v_add_co_u32_e32 v18, vcc, s23, v34
	v_pk_mul_f32 v[14:15], v[14:15], v[162:163] op_sel_hi:[1,0]
	s_nop 0
	v_addc_co_u32_e32 v19, vcc, 0, v35, vcc
	global_store_dwordx2 v[18:19], v[16:17], off
	v_pk_mul_f32 v[12:13], v[12:13], v[162:163] op_sel_hi:[1,0]
	v_pk_mul_f32 v[10:11], v[10:11], v[162:163] op_sel_hi:[1,0]
	v_pk_mul_f32 v[16:17], v[8:9], v[162:163] op_sel_hi:[1,0]
	v_pk_mul_f32 v[0:1], v[0:1], v[162:163] op_sel_hi:[1,0]
	v_pk_mul_f32 v[2:3], v[2:3], v[162:163] op_sel_hi:[1,0]
	v_pk_mul_f32 v[8:9], v[10:11], v[14:15]
	v_pk_mul_f32 v[10:11], v[16:17], v[12:13]
	v_mul_f32_e32 v12, 0xbfb8aa3b, v0
	v_mul_f32_e32 v13, 0xbfb8aa3b, v1
	v_mul_f32_e32 v14, 0xbfb8aa3b, v2
	v_mul_f32_e32 v15, 0xbfb8aa3b, v3
	v_exp_f32_e32 v12, v12
	v_exp_f32_e32 v13, v13
	v_exp_f32_e32 v14, v14
	v_exp_f32_e32 v15, v15
	v_add_f32_e32 v12, 1.0, v12
	v_add_f32_e32 v13, 1.0, v13
	v_add_f32_e32 v14, 1.0, v14
	v_add_f32_e32 v15, 1.0, v15
	v_rcp_f32_e32 v12, v12
	v_rcp_f32_e32 v13, v13
	v_rcp_f32_e32 v14, v14
	v_rcp_f32_e32 v15, v15
	v_pk_mul_f32 v[6:7], v[6:7], v[162:163] op_sel_hi:[1,0]
	v_pk_mul_f32 v[4:5], v[4:5], v[162:163] op_sel_hi:[1,0]
	v_mov_b32_dpp v20, v10 row_ror:2 row_mask:0xf bank_mask:0xf
	v_mov_b32_dpp v21, v11 row_ror:2 row_mask:0xf bank_mask:0xf
	v_mov_b32_dpp v22, v8 row_ror:2 row_mask:0xf bank_mask:0xf
	v_mov_b32_dpp v23, v9 row_ror:2 row_mask:0xf bank_mask:0xf
	v_pk_mul_f32 v[2:3], v[6:7], v[2:3]
	v_pk_mul_f32 v[0:1], v[4:5], v[0:1]
	v_mov_b32_dpp v16, v10 row_ror:1 row_mask:0xf bank_mask:0xf
	v_mov_b32_dpp v17, v11 row_ror:1 row_mask:0xf bank_mask:0xf
	v_mov_b32_dpp v18, v8 row_ror:1 row_mask:0xf bank_mask:0xf
	v_mov_b32_dpp v19, v9 row_ror:1 row_mask:0xf bank_mask:0xf
	v_pk_mul_f32 v[2:3], v[2:3], v[14:15]
	v_pk_mul_f32 v[0:1], v[0:1], v[12:13]
	v_cndmask_b32_e64 v13, v23, v41, s[4:5]
	v_cndmask_b32_e64 v12, v22, v40, s[4:5]
	v_cndmask_b32_e64 v15, v21, v39, s[4:5]
	v_cndmask_b32_e64 v14, v20, v38, s[4:5]
	v_cndmask_b32_e64 v5, v19, v37, s[2:3]
	v_cndmask_b32_e64 v4, v18, v36, s[2:3]
	v_cndmask_b32_e64 v7, v17, v33, s[2:3]
	v_cndmask_b32_e64 v6, v16, v32, s[2:3]
	v_pk_fma_f32 v[12:13], v[98:99], v[12:13], v[114:115]
	v_pk_fma_f32 v[14:15], v[96:97], v[14:15], v[112:113]
	v_pk_fma_f32 v[4:5], v[102:103], v[4:5], v[12:13]
	v_pk_fma_f32 v[6:7], v[100:101], v[6:7], v[14:15]
	v_pk_fma_f32 v[4:5], v[106:107], v[8:9], v[4:5]
	v_pk_fma_f32 v[6:7], v[104:105], v[10:11], v[6:7]
	v_pk_mul_f32 v[2:3], v[2:3], v[4:5]
	v_pk_mul_f32 v[0:1], v[0:1], v[6:7]
	s_nop 0
	v_cvt_pk_bf16_f32 v0, v0, v1
	v_cvt_pk_bf16_f32 v1, v2, v3
	v_add_co_u32_e32 v2, vcc, 0xb0000, v34
	s_nop 1
	v_addc_co_u32_e32 v3, vcc, 0, v35, vcc
	global_store_dwordx2 v[2:3], v[0:1], off
	s_and_saveexec_b64 s[34:35], s[6:7]
	s_cbranch_execz .LBB0_160
	v_lshl_add_u64 v[2:3], v[152:153], 0, s[8:9]
	v_cvt_pk_bf16_f32 v0, v10, v11
	v_cvt_pk_bf16_f32 v1, v8, v9
	v_lshl_add_u64 v[2:3], v[160:161], 1, v[2:3]
	global_store_dwordx2 v[2:3], v[0:1], off

;     __host__ __device__ bool next(int i, Unit& u) const {
;     ...
;         int wgid = (int)L; { const int q = nwg / NXCD, r = nwg % NXCD, xcd = wgid % NXCD, off = wgid / NXCD; wgid = (xcd < r ? xcd * (q + 1) : r * (q + 1) + (xcd - r) * q) + off; }
;         const int nig = WGM * nN, gid = wgid / nig, fm = gid * WGM, gsz = (nM - fm) < WGM ? (nM - fm) : WGM;
;         u.pm = fm + ((wgid % nig) % gsz); u.pn = (wgid % nig) / gsz; return true;
.LBB0_305:
	s_ashr_i32 s7, s7, 3
	s_add_i32 s7, s21, s7
	s_ashr_i32 s18, s7, 31
	s_lshr_b32 s18, s18, 26
	s_add_i32 s18, s7, s18
	s_ashr_i32 s19, s18, 6
	s_lshl_b32 s19, s19, 3
	s_andn2_b32 s18, s18, 63
	s_sub_i32 s7, s7, s18
	s_lshr_b32 s18, s7, 3
	s_and_b32 s7, s7, 7
	s_add_i32 s20, s19, s7

;     __host__ __device__ bool next(int i, Unit& u) const {
;     ...
;         int wgid = (int)L; { const int q = nwg / NXCD, r = nwg % NXCD, xcd = wgid % NXCD, off = wgid / NXCD; wgid = (xcd < r ? xcd * (q + 1) : r * (q + 1) + (xcd - r) * q) + off; }
;         const int nig = WGM * nN, gid = wgid / nig, fm = gid * WGM, gsz = (nM - fm) < WGM ? (nM - fm) : WGM;
;         u.pm = fm + ((wgid % nig) % gsz); u.pn = (wgid % nig) / gsz; return true;
.LBB0_1370:
	s_ashr_i32 s26, s28, 3
	s_add_i32 s26, s30, s26
	s_ashr_i32 s27, s26, 31
	s_lshr_b32 s27, s27, 24
	s_add_i32 s27, s26, s27
	s_ashr_i32 s28, s27, 8
	s_lshl_b32 s28, s28, 3
	s_and_b32 s27, s27, 0xffffff00
	s_sub_i32 s27, s26, s27
	s_lshr_b32 s26, s27, 3
	s_and_b32 s27, s27, 7
	s_add_i32 s28, s28, s27
	s_mov_b64 s[30:31], -1
	s_branch .LBB0_1372

; __device__ __forceinline__ unsigned cvt_pk_bf16(float lo, float hi) { f32x2 v = {lo, hi}; return __builtin_bit_cast(unsigned, __builtin_convertvector(v, bf2_t)); }
;     template <int CTRL> static __device__ __forceinline__ f32x4 rorv(const f32x4 v) { f32x4 o; o.x = dppf<CTRL>(v.x); o.y = dppf<CTRL>(v.y); o.z = dppf<CTRL>(v.z); o.w = dppf<CTRL>(v.w); return o; }
;     __device__ __forceinline__ void operator()(const f32x4 (&acc)[2][2][4][2], const Unit& u, int wr, int wc, int fr, int fq) const {
;     ...
;         const f32x4 w0 = *(const f32x4*)(cw + ch), w1 = *(const f32x4*)(cw + 2048 + ch), w2 = *(const f32x4*)(cw + 4096 + ch), bb = *(const f32x4*)(cb + ch);
; #pragma unroll
;         for (int ai = 0; ai < 2; ++ai) {
;             const int slab = u.pm * 4 + ai * 2 + wr;
;             f32x4 vprev = {0.f, 0.f, 0.f, 0.f};
; #pragma unroll
;             for (int m = 0; m < 4; ++m) {
;                 const int row = row0 + ai * HALF + m * 16;
;                 const float rs = rsv[ai][m];
;                 const f32x4 b = acc[ai][0][m][0] * rs, c = acc[ai][0][m][1] * rs, uu = acc[ai][1][m][0] * rs, g = acc[ai][1][m][1] * rs;
;                 const f32x4 v = c * uu;
;                 f32x4 sg;
; #pragma unroll
;                 for (int e = 0; e < 4; ++e) sg[e] = b[e] * g[e] * __builtin_amdgcn_rcpf(1.f + __expf(-g[e]));
;                 const f32x4 a1 = rorv<0x121>(v), a2 = rorv<0x122>(v), q1 = rorv<0x121>(vprev), q2 = rorv<0x122>(vprev);
;                 const f32x4 p1 = (fr == 0) ? q1 : a1, p2 = (fr < 2) ? q2 : a2;
;                 const f32x4 y = sg * (bb + w0 * p2 + w1 * p1 + w2 * v);
;                 u2 wy; wy.x = cvt_pk_bf16(y[0], y[1]); wy.y = cvt_pk_bf16(y[2], y[3]);
;                 u2 wv; wv.x = cvt_pk_bf16(v[0], v[1]); wv.y = cvt_pk_bf16(v[2], v[3]);
;                 if (m == 0) {
;                     if (fr >= 2) *(u2*)(Y + (size_t)row * 2048 + ch) = wy;
;                     else { u2 ws; ws.x = cvt_pk_bf16(sg[0], sg[1]); ws.y = cvt_pk_bf16(sg[2], sg[3]);
;                            *(u2*)(VB + ((size_t)slab * 4 + 2 + fr) * 2048 + ch) = wv; *(u2*)(BGB + ((size_t)slab * 2 + fr) * 2048 + ch) = ws; }
.LBB0_1392:
	v_lshl_or_b32 v160, s40, 6, v169
	v_ashrrev_i32_e32 v161, 31, v160
	v_lshlrev_b64 v[120:121], 2, v[160:161]
	v_lshl_add_u64 v[108:109], s[12:13], 0, v[120:121]
	v_lshl_add_u64 v[110:111], s[22:23], 0, v[120:121]
	v_lshl_add_u64 v[112:113], s[24:25], 0, v[120:121]
	v_lshl_add_u64 v[120:121], s[14:15], 0, v[120:121]
	global_load_dwordx4 v[116:119], v[108:109], off
	s_nop 0
	global_load_dwordx4 v[108:111], v[110:111], off
	s_waitcnt vmcnt(0)
	v_pk_mul_f32 v[132:133], v[132:133], v[180:181] op_sel_hi:[1,0]
	global_load_dwordx4 v[112:115], v[112:113], off
	v_mul_f32_e32 v181, 0xbfb8aa3b, v133
	global_load_dwordx4 v[120:123], v[120:121], off
	v_exp_f32_e32 v181, v181
	v_mul_f32_e32 v179, 0xbfb8aa3b, v132
	v_exp_f32_e32 v179, v179
	s_lshl_b32 s8, s38, 2
	v_pk_mul_f32 v[140:141], v[140:141], v[180:181] op_sel_hi:[1,0]
	v_pk_mul_f32 v[136:137], v[136:137], v[180:181] op_sel_hi:[1,0]
	v_pk_mul_f32 v[132:133], v[140:141], v[132:133]
	v_pk_mul_f32 v[140:141], v[134:135], v[180:181] op_sel_hi:[1,0]
	v_add_f32_e32 v179, 1.0, v179
	v_mul_f32_e32 v134, 0xbfb8aa3b, v140
	v_exp_f32_e32 v134, v134
	v_mul_f32_e32 v135, 0xbfb8aa3b, v141
	v_exp_f32_e32 v135, v135
	v_rcp_f32_e32 v182, v179
	v_add_f32_e32 v179, 1.0, v181
	v_rcp_f32_e32 v183, v179
	v_add_f32_e32 v134, 1.0, v134
	v_rcp_f32_e32 v184, v134
	v_add_f32_e32 v134, 1.0, v135
	v_rcp_f32_e32 v185, v134
	v_pk_mul_f32 v[134:135], v[132:133], v[182:183]
	v_pk_mul_f32 v[132:133], v[142:143], v[180:181] op_sel_hi:[1,0]
	v_pk_mul_f32 v[130:131], v[130:131], v[180:181] op_sel_hi:[1,0]
	v_pk_mul_f32 v[132:133], v[132:133], v[140:141]
	v_pk_mul_f32 v[128:129], v[128:129], v[180:181] op_sel_hi:[1,0]
	v_pk_mul_f32 v[140:141], v[132:133], v[184:185]
	v_pk_mul_f32 v[132:133], v[138:139], v[180:181] op_sel_hi:[1,0]
	s_add_i32 s8, s8, s33
	v_pk_mul_f32 v[132:133], v[132:133], v[130:131]
	v_pk_mul_f32 v[130:131], v[136:137], v[128:129]
	s_ashr_i32 s9, s8, 31
	s_lshl_b64 s[38:39], s[8:9], 14
	v_mov_b32_dpp v128, v130 row_ror:1 row_mask:0xf bank_mask:0xf
	v_mov_b32_dpp v129, v131 row_ror:1 row_mask:0xf bank_mask:0xf
	v_mov_b32_dpp v138, v132 row_ror:1 row_mask:0xf bank_mask:0xf
	v_mov_b32_dpp v139, v133 row_ror:1 row_mask:0xf bank_mask:0xf
	v_mov_b32_dpp v142, v130 row_ror:2 row_mask:0xf bank_mask:0xf
	v_mov_b32_dpp v143, v131 row_ror:2 row_mask:0xf bank_mask:0xf
	v_mov_b32_dpp v182, v132 row_ror:2 row_mask:0xf bank_mask:0xf
	v_mov_b32_dpp v183, v133 row_ror:2 row_mask:0xf bank_mask:0xf
	s_and_saveexec_b64 s[40:41], s[4:5]
	s_xor_b64 s[40:41], exec, s[40:41]
	s_cbranch_execz .LBB0_1394
	v_cvt_pk_bf16_f32 v136, v134, v135
	v_lshl_add_u64 v[134:135], v[148:149], 0, s[38:39]
	v_lshl_add_u64 v[134:135], v[160:161], 1, v[134:135]
	v_add_co_u32_e32 v134, vcc, 0x2000, v134
	v_cvt_pk_bf16_f32 v128, v130, v131
	v_cvt_pk_bf16_f32 v129, v132, v133
	s_lshl_b64 s[42:43], s[8:9], 13
	v_addc_co_u32_e32 v135, vcc, 0, v135, vcc
	v_cvt_pk_bf16_f32 v137, v140, v141
	global_store_dwordx2 v[134:135], v[128:129], off
	v_lshl_add_u64 v[180:181], v[150:151], 0, s[42:43]

; __device__ __forceinline__ unsigned cvt_pk_bf16(float lo, float hi) { f32x2 v = {lo, hi}; return __builtin_bit_cast(unsigned, __builtin_convertvector(v, bf2_t)); }
;     template <int CTRL> static __device__ __forceinline__ f32x4 rorv(const f32x4 v) { f32x4 o; o.x = dppf<CTRL>(v.x); o.y = dppf<CTRL>(v.y); o.z = dppf<CTRL>(v.z); o.w = dppf<CTRL>(v.w); return o; }
;     __device__ __forceinline__ void operator()(const f32x4 (&acc)[2][2][4][2], const Unit& u, int wr, int wc, int fr, int fq) const {
;     ...
;             for (int m = 0; m < 4; ++m) {
;                 const int row = row0 + ai * HALF + m * 16;
;                 const float rs = rsv[ai][m];
;                 const f32x4 b = acc[ai][0][m][0] * rs, c = acc[ai][0][m][1] * rs, uu = acc[ai][1][m][0] * rs, g = acc[ai][1][m][1] * rs;
;                 const f32x4 v = c * uu;
;                 f32x4 sg;
; #pragma unroll
;                 for (int e = 0; e < 4; ++e) sg[e] = b[e] * g[e] * __builtin_amdgcn_rcpf(1.f + __expf(-g[e]));
;                 const f32x4 a1 = rorv<0x121>(v), a2 = rorv<0x122>(v), q1 = rorv<0x121>(vprev), q2 = rorv<0x122>(vprev);
;                 const f32x4 p1 = (fr == 0) ? q1 : a1, p2 = (fr < 2) ? q2 : a2;
;                 const f32x4 y = sg * (bb + w0 * p2 + w1 * p1 + w2 * v);
;                 u2 wy; wy.x = cvt_pk_bf16(y[0], y[1]); wy.y = cvt_pk_bf16(y[2], y[3]);
;                 u2 wv; wv.x = cvt_pk_bf16(v[0], v[1]); wv.y = cvt_pk_bf16(v[2], v[3]);
;                 if (m == 0) {
;                     if (fr >= 2) *(u2*)(Y + (size_t)row * 2048 + ch) = wy;
;                     else { u2 ws; ws.x = cvt_pk_bf16(sg[0], sg[1]); ws.y = cvt_pk_bf16(sg[2], sg[3]);
;                            *(u2*)(VB + ((size_t)slab * 4 + 2 + fr) * 2048 + ch) = wv; *(u2*)(BGB + ((size_t)slab * 2 + fr) * 2048 + ch) = ws; }
;                 } else {
;                     *(u2*)(Y + (size_t)row * 2048 + ch) = wy;
;                     if (m == 3 && fr >= 14) *(u2*)(VB + ((size_t)slab * 4 + (fr - 14)) * 2048 + ch) = wv;
;                 }
.LBB0_1396:
	s_or_b64 exec, exec, s[40:41]
	v_pk_mul_f32 v[126:127], v[126:127], v[178:179] op_sel_hi:[1,0]
	v_pk_mul_f32 v[124:125], v[124:125], v[178:179] op_sel_hi:[1,0]
	v_pk_mul_f32 v[106:107], v[106:107], v[178:179] op_sel_hi:[1,0]
	v_pk_mul_f32 v[104:105], v[104:105], v[178:179] op_sel_hi:[1,0]
	v_pk_mul_f32 v[106:107], v[126:127], v[106:107]
	v_pk_mul_f32 v[104:105], v[124:125], v[104:105]
	v_mov_b32_dpp v179, v132 row_ror:1 row_mask:0xf bank_mask:0xf
	v_pk_mul_f32 v[96:97], v[96:97], v[178:179] op_sel_hi:[1,0]
	v_pk_mul_f32 v[98:99], v[98:99], v[178:179] op_sel_hi:[1,0]
	v_mul_f32_e32 v124, 0xbfb8aa3b, v96
	v_mul_f32_e32 v125, 0xbfb8aa3b, v97
	v_mul_f32_e32 v126, 0xbfb8aa3b, v98
	v_mul_f32_e32 v127, 0xbfb8aa3b, v99
	v_exp_f32_e32 v124, v124
	v_exp_f32_e32 v125, v125
	v_exp_f32_e32 v126, v126
	v_exp_f32_e32 v127, v127
	v_add_f32_e32 v124, 1.0, v124
	v_add_f32_e32 v125, 1.0, v125
	v_add_f32_e32 v126, 1.0, v126
	v_add_f32_e32 v127, 1.0, v127
	v_rcp_f32_e32 v124, v124
	v_rcp_f32_e32 v125, v125
	v_rcp_f32_e32 v126, v126
	v_rcp_f32_e32 v127, v127
	v_lshlrev_b64 v[128:129], 1, v[160:161]
	v_lshl_add_u64 v[134:135], v[180:181], 0, v[128:129]
	v_pk_mul_f32 v[102:103], v[102:103], v[178:179] op_sel_hi:[1,0]
	v_pk_mul_f32 v[100:101], v[100:101], v[178:179] op_sel_hi:[1,0]
	global_store_dwordx2 v[134:135], v[136:137], off
	v_mov_b32_dpp v138, v104 row_ror:2 row_mask:0xf bank_mask:0xf
	v_mov_b32_dpp v139, v105 row_ror:2 row_mask:0xf bank_mask:0xf
	v_mov_b32_dpp v140, v106 row_ror:2 row_mask:0xf bank_mask:0xf
	v_mov_b32_dpp v141, v107 row_ror:2 row_mask:0xf bank_mask:0xf
	v_mov_b32_e32 v142, v130
	v_mov_b32_e32 v143, v131
	v_mov_b32_e32 v180, v133
	v_mov_b32_dpp v130, v130 row_ror:2 row_mask:0xf bank_mask:0xf
	v_mov_b32_dpp v131, v131 row_ror:2 row_mask:0xf bank_mask:0xf
	v_mov_b32_dpp v132, v132 row_ror:2 row_mask:0xf bank_mask:0xf
	v_mov_b32_dpp v133, v133 row_ror:2 row_mask:0xf bank_mask:0xf
	v_pk_mul_f32 v[98:99], v[102:103], v[98:99]
	v_pk_mul_f32 v[96:97], v[100:101], v[96:97]
	v_mov_b32_dpp v134, v104 row_ror:1 row_mask:0xf bank_mask:0xf
	v_mov_b32_dpp v135, v105 row_ror:1 row_mask:0xf bank_mask:0xf
	v_mov_b32_dpp v136, v106 row_ror:1 row_mask:0xf bank_mask:0xf
	v_mov_b32_dpp v137, v107 row_ror:1 row_mask:0xf bank_mask:0xf
	v_mov_b32_dpp v142, v142 row_ror:1 row_mask:0xf bank_mask:0xf
	v_mov_b32_dpp v143, v143 row_ror:1 row_mask:0xf bank_mask:0xf
	v_mov_b32_dpp v180, v180 row_ror:1 row_mask:0xf bank_mask:0xf
	v_pk_mul_f32 v[98:99], v[98:99], v[126:127]
	v_pk_mul_f32 v[96:97], v[96:97], v[124:125]
	v_cndmask_b32_e64 v125, v141, v133, s[4:5]
	v_cndmask_b32_e64 v124, v140, v132, s[4:5]
	v_cndmask_b32_e64 v127, v139, v131, s[4:5]
	v_cndmask_b32_e64 v126, v138, v130, s[4:5]
	v_pk_mul_f32 v[94:95], v[94:95], v[176:177] op_sel_hi:[1,0]
	v_pk_mul_f32 v[92:93], v[92:93], v[176:177] op_sel_hi:[1,0]
	v_pk_mul_f32 v[90:91], v[90:91], v[176:177] op_sel_hi:[1,0]
	v_pk_mul_f32 v[88:89], v[88:89], v[176:177] op_sel_hi:[1,0]
	v_pk_mul_f32 v[80:81], v[80:81], v[176:177] op_sel_hi:[1,0]
	v_pk_mul_f32 v[82:83], v[82:83], v[176:177] op_sel_hi:[1,0]
	v_cndmask_b32_e64 v101, v137, v180, s[2:3]
	v_cndmask_b32_e64 v100, v136, v179, s[2:3]
	v_cndmask_b32_e64 v103, v135, v143, s[2:3]
	v_cndmask_b32_e64 v102, v134, v142, s[2:3]
	s_waitcnt vmcnt(1)
	v_pk_fma_f32 v[124:125], v[118:119], v[124:125], v[122:123]
	v_pk_fma_f32 v[126:127], v[116:117], v[126:127], v[120:121]
	v_pk_mul_f32 v[90:91], v[90:91], v[94:95]
	v_pk_mul_f32 v[88:89], v[88:89], v[92:93]
	v_mul_f32_e32 v92, 0xbfb8aa3b, v80
	v_mul_f32_e32 v93, 0xbfb8aa3b, v81
	v_mul_f32_e32 v94, 0xbfb8aa3b, v82
	v_mul_f32_e32 v95, 0xbfb8aa3b, v83
	v_pk_fma_f32 v[100:101], v[110:111], v[100:101], v[124:125]
	v_pk_fma_f32 v[102:103], v[108:109], v[102:103], v[126:127]
	v_exp_f32_e32 v92, v92
	v_exp_f32_e32 v93, v93
	v_exp_f32_e32 v94, v94
	v_exp_f32_e32 v95, v95
	v_pk_fma_f32 v[100:101], v[106:107], v[114:115], v[100:101]
	v_pk_fma_f32 v[102:103], v[104:105], v[112:113], v[102:103]
	v_pk_mul_f32 v[98:99], v[98:99], v[100:101]
	v_pk_mul_f32 v[96:97], v[96:97], v[102:103]
	v_add_f32_e32 v92, 1.0, v92
	v_cvt_pk_bf16_f32 v96, v96, v97
	v_cvt_pk_bf16_f32 v97, v98, v99
	v_or_b32_e32 v98, 16, v164
	v_ashrrev_i32_e32 v99, 31, v98
	v_add_f32_e32 v93, 1.0, v93
	v_add_f32_e32 v94, 1.0, v94
	v_add_f32_e32 v95, 1.0, v95
	v_lshlrev_b64 v[98:99], 12, v[98:99]
	v_rcp_f32_e32 v92, v92
	v_rcp_f32_e32 v93, v93
	v_rcp_f32_e32 v94, v94
	v_rcp_f32_e32 v95, v95
	v_lshl_add_u64 v[98:99], s[60:61], 0, v[98:99]
	v_lshl_add_u64 v[98:99], v[98:99], 0, v[128:129]
	v_pk_mul_f32 v[86:87], v[86:87], v[176:177] op_sel_hi:[1,0]
	v_pk_mul_f32 v[84:85], v[84:85], v[176:177] op_sel_hi:[1,0]
	global_store_dwordx2 v[98:99], v[96:97], off
	v_mov_b32_dpp v100, v88 row_ror:2 row_mask:0xf bank_mask:0xf
	v_mov_b32_dpp v101, v89 row_ror:2 row_mask:0xf bank_mask:0xf
	v_mov_b32_dpp v102, v90 row_ror:2 row_mask:0xf bank_mask:0xf
	v_mov_b32_dpp v103, v91 row_ror:2 row_mask:0xf bank_mask:0xf
	v_pk_mul_f32 v[82:83], v[86:87], v[82:83]
	v_pk_mul_f32 v[80:81], v[84:85], v[80:81]
	v_mov_b32_dpp v96, v88 row_ror:1 row_mask:0xf bank_mask:0xf
	v_mov_b32_dpp v97, v89 row_ror:1 row_mask:0xf bank_mask:0xf
	v_mov_b32_dpp v98, v90 row_ror:1 row_mask:0xf bank_mask:0xf
	v_mov_b32_dpp v99, v91 row_ror:1 row_mask:0xf bank_mask:0xf
	v_pk_mul_f32 v[82:83], v[82:83], v[94:95]
	v_pk_mul_f32 v[80:81], v[80:81], v[92:93]
	v_cndmask_b32_e64 v93, v103, v141, s[4:5]
	v_cndmask_b32_e64 v92, v102, v140, s[4:5]
	v_cndmask_b32_e64 v95, v101, v139, s[4:5]
	v_cndmask_b32_e64 v94, v100, v138, s[4:5]
	v_cndmask_b32_e64 v85, v99, v137, s[2:3]
	v_cndmask_b32_e64 v84, v98, v136, s[2:3]
; __device__ __forceinline__ unsigned cvt_pk_bf16(float lo, float hi) { f32x2 v = {lo, hi}; return __builtin_bit_cast(unsigned, __builtin_convertvector(v, bf2_t)); }
;     template <int CTRL> static __device__ __forceinline__ f32x4 rorv(const f32x4 v) { f32x4 o; o.x = dppf<CTRL>(v.x); o.y = dppf<CTRL>(v.y); o.z = dppf<CTRL>(v.z); o.w = dppf<CTRL>(v.w); return o; }
;     __device__ __forceinline__ void operator()(const f32x4 (&acc)[2][2][4][2], const Unit& u, int wr, int wc, int fr, int fq) const {
;     ...
;             for (int m = 0; m < 4; ++m) {
;                 const int row = row0 + ai * HALF + m * 16;
;                 const float rs = rsv[ai][m];
;                 const f32x4 b = acc[ai][0][m][0] * rs, c = acc[ai][0][m][1] * rs, uu = acc[ai][1][m][0] * rs, g = acc[ai][1][m][1] * rs;
;                 const f32x4 v = c * uu;
;                 f32x4 sg;
; #pragma unroll
;                 for (int e = 0; e < 4; ++e) sg[e] = b[e] * g[e] * __builtin_amdgcn_rcpf(1.f + __expf(-g[e]));
;                 const f32x4 a1 = rorv<0x121>(v), a2 = rorv<0x122>(v), q1 = rorv<0x121>(vprev), q2 = rorv<0x122>(vprev);
;                 const f32x4 p1 = (fr == 0) ? q1 : a1, p2 = (fr < 2) ? q2 : a2;
;                 const f32x4 y = sg * (bb + w0 * p2 + w1 * p1 + w2 * v);
;                 u2 wy; wy.x = cvt_pk_bf16(y[0], y[1]); wy.y = cvt_pk_bf16(y[2], y[3]);
;                 u2 wv; wv.x = cvt_pk_bf16(v[0], v[1]); wv.y = cvt_pk_bf16(v[2], v[3]);
;                 if (m == 0) {
;                     if (fr >= 2) *(u2*)(Y + (size_t)row * 2048 + ch) = wy;
;                     else { u2 ws; ws.x = cvt_pk_bf16(sg[0], sg[1]); ws.y = cvt_pk_bf16(sg[2], sg[3]);
;                            *(u2*)(VB + ((size_t)slab * 4 + 2 + fr) * 2048 + ch) = wv; *(u2*)(BGB + ((size_t)slab * 2 + fr) * 2048 + ch) = ws; }
;                 } else {
;                     *(u2*)(Y + (size_t)row * 2048 + ch) = wy;
;                     if (m == 3 && fr >= 14) *(u2*)(VB + ((size_t)slab * 4 + (fr - 14)) * 2048 + ch) = wv;
;                 }
	v_cndmask_b32_e64 v87, v97, v135, s[2:3]
	v_cndmask_b32_e64 v86, v96, v134, s[2:3]
	v_pk_fma_f32 v[92:93], v[118:119], v[92:93], v[122:123]
	v_pk_fma_f32 v[94:95], v[116:117], v[94:95], v[120:121]
	v_pk_fma_f32 v[84:85], v[110:111], v[84:85], v[92:93]
	v_pk_fma_f32 v[86:87], v[108:109], v[86:87], v[94:95]
	v_pk_fma_f32 v[84:85], v[90:91], v[114:115], v[84:85]
	v_pk_fma_f32 v[86:87], v[88:89], v[112:113], v[86:87]
	v_pk_mul_f32 v[82:83], v[82:83], v[84:85]
	v_pk_mul_f32 v[80:81], v[80:81], v[86:87]
	v_pk_mul_f32 v[78:79], v[78:79], v[174:175] op_sel_hi:[1,0]
	v_cvt_pk_bf16_f32 v80, v80, v81
	v_cvt_pk_bf16_f32 v81, v82, v83
	v_or_b32_e32 v82, 32, v164
	v_ashrrev_i32_e32 v83, 31, v82
	v_lshlrev_b64 v[82:83], 12, v[82:83]
	v_lshl_add_u64 v[82:83], s[60:61], 0, v[82:83]
	v_lshl_add_u64 v[82:83], v[82:83], 0, v[128:129]
	global_store_dwordx2 v[82:83], v[80:81], off
	v_pk_mul_f32 v[76:77], v[76:77], v[174:175] op_sel_hi:[1,0]
	v_pk_mul_f32 v[74:75], v[74:75], v[174:175] op_sel_hi:[1,0]
	v_pk_mul_f32 v[80:81], v[72:73], v[174:175] op_sel_hi:[1,0]
	v_pk_mul_f32 v[64:65], v[64:65], v[174:175] op_sel_hi:[1,0]
	v_pk_mul_f32 v[66:67], v[66:67], v[174:175] op_sel_hi:[1,0]
	v_pk_mul_f32 v[72:73], v[74:75], v[78:79]
	v_pk_mul_f32 v[74:75], v[80:81], v[76:77]
	v_mul_f32_e32 v76, 0xbfb8aa3b, v64
	v_mul_f32_e32 v77, 0xbfb8aa3b, v65
	v_mul_f32_e32 v78, 0xbfb8aa3b, v66
	v_mul_f32_e32 v79, 0xbfb8aa3b, v67
	v_exp_f32_e32 v76, v76
	v_exp_f32_e32 v77, v77
	v_exp_f32_e32 v78, v78
	v_exp_f32_e32 v79, v79
	v_add_f32_e32 v76, 1.0, v76
	v_add_f32_e32 v77, 1.0, v77
	v_add_f32_e32 v78, 1.0, v78
	v_add_f32_e32 v79, 1.0, v79
	v_rcp_f32_e32 v76, v76
	v_rcp_f32_e32 v77, v77
	v_rcp_f32_e32 v78, v78
	v_rcp_f32_e32 v79, v79
	v_pk_mul_f32 v[70:71], v[70:71], v[174:175] op_sel_hi:[1,0]
	v_pk_mul_f32 v[68:69], v[68:69], v[174:175] op_sel_hi:[1,0]
	v_mov_b32_dpp v84, v74 row_ror:2 row_mask:0xf bank_mask:0xf
	v_mov_b32_dpp v85, v75 row_ror:2 row_mask:0xf bank_mask:0xf
	v_mov_b32_dpp v86, v72 row_ror:2 row_mask:0xf bank_mask:0xf
	v_mov_b32_dpp v87, v73 row_ror:2 row_mask:0xf bank_mask:0xf
	v_pk_mul_f32 v[66:67], v[70:71], v[66:67]
	v_pk_mul_f32 v[64:65], v[68:69], v[64:65]
	v_mov_b32_dpp v80, v74 row_ror:1 row_mask:0xf bank_mask:0xf
	v_mov_b32_dpp v81, v75 row_ror:1 row_mask:0xf bank_mask:0xf
	v_mov_b32_dpp v82, v72 row_ror:1 row_mask:0xf bank_mask:0xf
	v_mov_b32_dpp v83, v73 row_ror:1 row_mask:0xf bank_mask:0xf
	v_pk_mul_f32 v[66:67], v[66:67], v[78:79]
	v_pk_mul_f32 v[64:65], v[64:65], v[76:77]
	v_cndmask_b32_e64 v77, v87, v103, s[4:5]
	v_cndmask_b32_e64 v76, v86, v102, s[4:5]
	v_cndmask_b32_e64 v79, v85, v101, s[4:5]
	v_cndmask_b32_e64 v78, v84, v100, s[4:5]
	v_cndmask_b32_e64 v69, v83, v99, s[2:3]
	v_cndmask_b32_e64 v68, v82, v98, s[2:3]
	v_cndmask_b32_e64 v71, v81, v97, s[2:3]
	v_cndmask_b32_e64 v70, v80, v96, s[2:3]
	v_pk_fma_f32 v[76:77], v[118:119], v[76:77], v[122:123]
	v_pk_fma_f32 v[78:79], v[116:117], v[78:79], v[120:121]
	v_pk_fma_f32 v[68:69], v[110:111], v[68:69], v[76:77]
	v_pk_fma_f32 v[70:71], v[108:109], v[70:71], v[78:79]
	v_pk_fma_f32 v[68:69], v[72:73], v[114:115], v[68:69]
	v_pk_fma_f32 v[70:71], v[74:75], v[112:113], v[70:71]
	v_pk_mul_f32 v[66:67], v[66:67], v[68:69]
	v_pk_mul_f32 v[64:65], v[64:65], v[70:71]
	s_nop 0
	v_cvt_pk_bf16_f32 v64, v64, v65
	v_cvt_pk_bf16_f32 v65, v66, v67
	v_or_b32_e32 v66, 48, v164
	v_ashrrev_i32_e32 v67, 31, v66
	v_lshlrev_b64 v[66:67], 12, v[66:67]
	v_lshl_add_u64 v[66:67], s[60:61], 0, v[66:67]
	v_lshl_add_u64 v[66:67], v[66:67], 0, v[128:129]
	global_store_dwordx2 v[66:67], v[64:65], off
	s_and_saveexec_b64 s[40:41], s[6:7]
	s_cbranch_execz .LBB0_1398
	v_lshl_add_u64 v[66:67], v[152:153], 0, s[38:39]
	v_cvt_pk_bf16_f32 v64, v74, v75
	v_cvt_pk_bf16_f32 v65, v72, v73
	v_lshl_add_u64 v[66:67], v[160:161], 1, v[66:67]
	global_store_dwordx2 v[66:67], v[64:65], off
.LBB0_1398:
	s_or_b64 exec, exec, s[40:41]
	v_pk_mul_f32 v[52:53], v[52:53], v[172:173] op_sel_hi:[1,0]
	v_pk_mul_f32 v[60:61], v[60:61], v[172:173] op_sel_hi:[1,0]
	v_mul_f32_e32 v65, 0xbfb8aa3b, v53
	v_exp_f32_e32 v65, v65
	v_pk_mul_f32 v[54:55], v[54:55], v[172:173] op_sel_hi:[1,0]
	v_mul_f32_e32 v64, 0xbfb8aa3b, v52
	v_pk_mul_f32 v[52:53], v[60:61], v[52:53]
	v_add_f32_e32 v60, 1.0, v65
	v_mul_f32_e32 v61, 0xbfb8aa3b, v54
	v_mul_f32_e32 v65, 0xbfb8aa3b, v55
	v_exp_f32_e32 v61, v61
	v_exp_f32_e32 v66, v65
	v_exp_f32_e32 v64, v64
	v_rcp_f32_e32 v65, v60
	v_add_f32_e32 v60, 1.0, v61
	v_add_f32_e32 v61, 1.0, v66
	v_add_f32_e32 v64, 1.0, v64
	v_rcp_f32_e32 v60, v60
	v_rcp_f32_e32 v61, v61
	v_rcp_f32_e32 v64, v64
	v_pk_mul_f32 v[62:63], v[62:63], v[172:173] op_sel_hi:[1,0]
	v_pk_mul_f32 v[58:59], v[58:59], v[172:173] op_sel_hi:[1,0]
	v_pk_mul_f32 v[56:57], v[56:57], v[172:173] op_sel_hi:[1,0]
	v_pk_mul_f32 v[50:51], v[50:51], v[172:173] op_sel_hi:[1,0]
	v_pk_mul_f32 v[48:49], v[48:49], v[172:173] op_sel_hi:[1,0]
	s_add_i32 s38, s8, 2
	v_pk_mul_f32 v[54:55], v[62:63], v[54:55]
	v_pk_mul_f32 v[50:51], v[58:59], v[50:51]
	v_pk_mul_f32 v[48:49], v[56:57], v[48:49]
	s_ashr_i32 s39, s38, 31
	v_pk_mul_f32 v[54:55], v[54:55], v[60:61]
	s_lshl_b64 s[8:9], s[38:39], 14
	v_pk_mul_f32 v[52:53], v[52:53], v[64:65]
	v_mov_b32_dpp v56, v48 row_ror:1 row_mask:0xf bank_mask:0xf
	v_mov_b32_dpp v57, v49 row_ror:1 row_mask:0xf bank_mask:0xf
	v_mov_b32_dpp v60, v50 row_ror:1 row_mask:0xf bank_mask:0xf
	v_mov_b32_dpp v61, v51 row_ror:1 row_mask:0xf bank_mask:0xf
	v_mov_b32_dpp v62, v48 row_ror:2 row_mask:0xf bank_mask:0xf
	v_mov_b32_dpp v63, v49 row_ror:2 row_mask:0xf bank_mask:0xf
	v_mov_b32_dpp v66, v50 row_ror:2 row_mask:0xf bank_mask:0xf
	v_mov_b32_dpp v67, v51 row_ror:2 row_mask:0xf bank_mask:0xf
	s_and_saveexec_b64 s[40:41], s[4:5]
	s_xor_b64 s[40:41], exec, s[40:41]
	s_cbranch_execz .LBB0_1400
	v_cvt_pk_bf16_f32 v58, v52, v53
	v_lshl_add_u64 v[52:53], v[148:149], 0, s[8:9]
	v_lshl_add_u64 v[52:53], v[160:161], 1, v[52:53]
	s_lshl_b64 s[38:39], s[38:39], 13
	v_add_co_u32_e32 v52, vcc, 0x2000, v52
	v_cvt_pk_bf16_f32 v56, v48, v49
	v_cvt_pk_bf16_f32 v57, v50, v51
	v_cvt_pk_bf16_f32 v59, v54, v55
	v_addc_co_u32_e32 v53, vcc, 0, v53, vcc
	v_lshl_add_u64 v[64:65], v[150:151], 0, s[38:39]
	global_store_dwordx2 v[52:53], v[56:57], off

; __device__ __forceinline__ unsigned cvt_pk_bf16(float lo, float hi) { f32x2 v = {lo, hi}; return __builtin_bit_cast(unsigned, __builtin_convertvector(v, bf2_t)); }
;     template <int CTRL> static __device__ __forceinline__ f32x4 rorv(const f32x4 v) { f32x4 o; o.x = dppf<CTRL>(v.x); o.y = dppf<CTRL>(v.y); o.z = dppf<CTRL>(v.z); o.w = dppf<CTRL>(v.w); return o; }
;     __device__ __forceinline__ void operator()(const f32x4 (&acc)[2][2][4][2], const Unit& u, int wr, int wc, int fr, int fq) const {
;     ...
;             for (int m = 0; m < 4; ++m) {
;                 const int row = row0 + ai * HALF + m * 16;
;                 const float rs = rsv[ai][m];
;                 const f32x4 b = acc[ai][0][m][0] * rs, c = acc[ai][0][m][1] * rs, uu = acc[ai][1][m][0] * rs, g = acc[ai][1][m][1] * rs;
;                 const f32x4 v = c * uu;
;                 f32x4 sg;
; #pragma unroll
;                 for (int e = 0; e < 4; ++e) sg[e] = b[e] * g[e] * __builtin_amdgcn_rcpf(1.f + __expf(-g[e]));
;                 const f32x4 a1 = rorv<0x121>(v), a2 = rorv<0x122>(v), q1 = rorv<0x121>(vprev), q2 = rorv<0x122>(vprev);
;                 const f32x4 p1 = (fr == 0) ? q1 : a1, p2 = (fr < 2) ? q2 : a2;
;                 const f32x4 y = sg * (bb + w0 * p2 + w1 * p1 + w2 * v);
;                 u2 wy; wy.x = cvt_pk_bf16(y[0], y[1]); wy.y = cvt_pk_bf16(y[2], y[3]);
;                 u2 wv; wv.x = cvt_pk_bf16(v[0], v[1]); wv.y = cvt_pk_bf16(v[2], v[3]);
;                 if (m == 0) {
;                     if (fr >= 2) *(u2*)(Y + (size_t)row * 2048 + ch) = wy;
;                     else { u2 ws; ws.x = cvt_pk_bf16(sg[0], sg[1]); ws.y = cvt_pk_bf16(sg[2], sg[3]);
;                            *(u2*)(VB + ((size_t)slab * 4 + 2 + fr) * 2048 + ch) = wv; *(u2*)(BGB + ((size_t)slab * 2 + fr) * 2048 + ch) = ws; }
;                 } else {
;                     *(u2*)(Y + (size_t)row * 2048 + ch) = wy;
;                     if (m == 3 && fr >= 14) *(u2*)(VB + ((size_t)slab * 4 + (fr - 14)) * 2048 + ch) = wv;
;                 }
.LBB0_1402:
	s_or_b64 exec, exec, s[38:39]
	v_pk_mul_f32 v[46:47], v[46:47], v[168:169] op_sel_hi:[1,0]
	v_pk_mul_f32 v[44:45], v[44:45], v[168:169] op_sel_hi:[1,0]
	v_pk_mul_f32 v[42:43], v[42:43], v[168:169] op_sel_hi:[1,0]
	v_pk_mul_f32 v[40:41], v[40:41], v[168:169] op_sel_hi:[1,0]
	v_pk_mul_f32 v[32:33], v[32:33], v[168:169] op_sel_hi:[1,0]
	v_pk_mul_f32 v[34:35], v[34:35], v[168:169] op_sel_hi:[1,0]
	v_pk_mul_f32 v[42:43], v[46:47], v[42:43]
	v_pk_mul_f32 v[40:41], v[44:45], v[40:41]
	v_mul_f32_e32 v44, 0xbfb8aa3b, v32
	v_mul_f32_e32 v45, 0xbfb8aa3b, v33
	v_mul_f32_e32 v46, 0xbfb8aa3b, v34
	v_mul_f32_e32 v47, 0xbfb8aa3b, v35
	v_exp_f32_e32 v44, v44
	v_exp_f32_e32 v45, v45
	v_exp_f32_e32 v46, v46
	v_exp_f32_e32 v47, v47
	v_add_f32_e32 v44, 1.0, v44
	v_add_f32_e32 v45, 1.0, v45
	v_add_f32_e32 v46, 1.0, v46
	v_add_f32_e32 v47, 1.0, v47
	v_rcp_f32_e32 v44, v44
	v_rcp_f32_e32 v45, v45
	v_rcp_f32_e32 v46, v46
	v_rcp_f32_e32 v47, v47
	v_lshl_add_u64 v[52:53], v[64:65], 0, v[128:129]
	global_store_dwordx2 v[52:53], v[58:59], off
	v_pk_mul_f32 v[38:39], v[38:39], v[168:169] op_sel_hi:[1,0]
	v_pk_mul_f32 v[36:37], v[36:37], v[168:169] op_sel_hi:[1,0]
	v_mov_b32_dpp v56, v40 row_ror:2 row_mask:0xf bank_mask:0xf
	v_mov_b32_dpp v57, v41 row_ror:2 row_mask:0xf bank_mask:0xf
	v_mov_b32_dpp v58, v42 row_ror:2 row_mask:0xf bank_mask:0xf
	v_mov_b32_dpp v59, v43 row_ror:2 row_mask:0xf bank_mask:0xf
	v_mov_b32_e32 v60, v48
	v_mov_b32_e32 v61, v49
	v_mov_b32_e32 v62, v50
	v_mov_b32_e32 v63, v51
	v_mov_b32_dpp v48, v48 row_ror:2 row_mask:0xf bank_mask:0xf
	v_mov_b32_dpp v49, v49 row_ror:2 row_mask:0xf bank_mask:0xf
	v_mov_b32_dpp v50, v50 row_ror:2 row_mask:0xf bank_mask:0xf
	v_mov_b32_dpp v51, v51 row_ror:2 row_mask:0xf bank_mask:0xf
	v_pk_mul_f32 v[34:35], v[38:39], v[34:35]
	v_pk_mul_f32 v[32:33], v[36:37], v[32:33]
	v_mov_b32_dpp v52, v40 row_ror:1 row_mask:0xf bank_mask:0xf
	v_mov_b32_dpp v53, v41 row_ror:1 row_mask:0xf bank_mask:0xf
	v_mov_b32_dpp v54, v42 row_ror:1 row_mask:0xf bank_mask:0xf
	v_mov_b32_dpp v55, v43 row_ror:1 row_mask:0xf bank_mask:0xf
	v_mov_b32_dpp v60, v60 row_ror:1 row_mask:0xf bank_mask:0xf
	v_mov_b32_dpp v61, v61 row_ror:1 row_mask:0xf bank_mask:0xf
	v_mov_b32_dpp v62, v62 row_ror:1 row_mask:0xf bank_mask:0xf
	v_mov_b32_dpp v63, v63 row_ror:1 row_mask:0xf bank_mask:0xf
	v_pk_mul_f32 v[34:35], v[34:35], v[46:47]
	v_pk_mul_f32 v[32:33], v[32:33], v[44:45]
	v_cndmask_b32_e64 v45, v59, v51, s[4:5]
	v_cndmask_b32_e64 v44, v58, v50, s[4:5]
	v_cndmask_b32_e64 v47, v57, v49, s[4:5]
	v_cndmask_b32_e64 v46, v56, v48, s[4:5]
	v_pk_mul_f32 v[30:31], v[30:31], v[166:167] op_sel_hi:[1,0]
	v_pk_mul_f32 v[28:29], v[28:29], v[166:167] op_sel_hi:[1,0]
	v_pk_mul_f32 v[26:27], v[26:27], v[166:167] op_sel_hi:[1,0]
	v_pk_mul_f32 v[24:25], v[24:25], v[166:167] op_sel_hi:[1,0]
	v_pk_mul_f32 v[16:17], v[16:17], v[166:167] op_sel_hi:[1,0]
	v_pk_mul_f32 v[18:19], v[18:19], v[166:167] op_sel_hi:[1,0]
	v_cndmask_b32_e64 v37, v55, v63, s[2:3]
	v_cndmask_b32_e64 v36, v54, v62, s[2:3]
	v_cndmask_b32_e64 v39, v53, v61, s[2:3]
	v_cndmask_b32_e64 v38, v52, v60, s[2:3]
	v_pk_fma_f32 v[44:45], v[118:119], v[44:45], v[122:123]
	v_pk_fma_f32 v[46:47], v[116:117], v[46:47], v[120:121]
	v_pk_mul_f32 v[26:27], v[26:27], v[30:31]
	v_pk_mul_f32 v[24:25], v[24:25], v[28:29]
	v_mul_f32_e32 v28, 0xbfb8aa3b, v16
	v_mul_f32_e32 v29, 0xbfb8aa3b, v17
	v_mul_f32_e32 v30, 0xbfb8aa3b, v18
	v_mul_f32_e32 v31, 0xbfb8aa3b, v19
	v_pk_fma_f32 v[36:37], v[110:111], v[36:37], v[44:45]
	v_pk_fma_f32 v[38:39], v[108:109], v[38:39], v[46:47]
	v_exp_f32_e32 v28, v28
	v_exp_f32_e32 v29, v29
	v_exp_f32_e32 v30, v30
	v_exp_f32_e32 v31, v31
	v_pk_fma_f32 v[36:37], v[42:43], v[114:115], v[36:37]
	v_pk_fma_f32 v[38:39], v[40:41], v[112:113], v[38:39]
	v_pk_mul_f32 v[34:35], v[34:35], v[36:37]
	v_pk_mul_f32 v[32:33], v[32:33], v[38:39]
	v_add_f32_e32 v28, 1.0, v28
	v_cvt_pk_bf16_f32 v32, v32, v33
	v_cvt_pk_bf16_f32 v33, v34, v35
	v_lshlrev_b64 v[34:35], 12, v[164:165]
	v_lshl_add_u64 v[34:35], s[60:61], 0, v[34:35]
	v_add_f32_e32 v29, 1.0, v29
	v_add_f32_e32 v30, 1.0, v30
	v_add_f32_e32 v31, 1.0, v31
	v_lshl_add_u64 v[34:35], v[34:35], 0, v[128:129]
	v_rcp_f32_e32 v28, v28
	v_rcp_f32_e32 v29, v29
	v_rcp_f32_e32 v30, v30
	v_rcp_f32_e32 v31, v31
	v_add_co_u32_e32 v36, vcc, s64, v34
	s_nop 0
	v_addc_co_u32_e32 v37, vcc, 0, v35, vcc
	v_pk_mul_f32 v[22:23], v[22:23], v[166:167] op_sel_hi:[1,0]
	v_pk_mul_f32 v[20:21], v[20:21], v[166:167] op_sel_hi:[1,0]
; __device__ __forceinline__ unsigned cvt_pk_bf16(float lo, float hi) { f32x2 v = {lo, hi}; return __builtin_bit_cast(unsigned, __builtin_convertvector(v, bf2_t)); }
;     template <int CTRL> static __device__ __forceinline__ f32x4 rorv(const f32x4 v) { f32x4 o; o.x = dppf<CTRL>(v.x); o.y = dppf<CTRL>(v.y); o.z = dppf<CTRL>(v.z); o.w = dppf<CTRL>(v.w); return o; }
;     __device__ __forceinline__ void operator()(const f32x4 (&acc)[2][2][4][2], const Unit& u, int wr, int wc, int fr, int fq) const {
;     ...
;             for (int m = 0; m < 4; ++m) {
;                 const int row = row0 + ai * HALF + m * 16;
;                 const float rs = rsv[ai][m];
;                 const f32x4 b = acc[ai][0][m][0] * rs, c = acc[ai][0][m][1] * rs, uu = acc[ai][1][m][0] * rs, g = acc[ai][1][m][1] * rs;
;                 const f32x4 v = c * uu;
;                 f32x4 sg;
; #pragma unroll
;                 for (int e = 0; e < 4; ++e) sg[e] = b[e] * g[e] * __builtin_amdgcn_rcpf(1.f + __expf(-g[e]));
;                 const f32x4 a1 = rorv<0x121>(v), a2 = rorv<0x122>(v), q1 = rorv<0x121>(vprev), q2 = rorv<0x122>(vprev);
;                 const f32x4 p1 = (fr == 0) ? q1 : a1, p2 = (fr < 2) ? q2 : a2;
;                 const f32x4 y = sg * (bb + w0 * p2 + w1 * p1 + w2 * v);
;                 u2 wy; wy.x = cvt_pk_bf16(y[0], y[1]); wy.y = cvt_pk_bf16(y[2], y[3]);
;                 u2 wv; wv.x = cvt_pk_bf16(v[0], v[1]); wv.y = cvt_pk_bf16(v[2], v[3]);
;                 if (m == 0) {
;                     if (fr >= 2) *(u2*)(Y + (size_t)row * 2048 + ch) = wy;
;                     else { u2 ws; ws.x = cvt_pk_bf16(sg[0], sg[1]); ws.y = cvt_pk_bf16(sg[2], sg[3]);
;                            *(u2*)(VB + ((size_t)slab * 4 + 2 + fr) * 2048 + ch) = wv; *(u2*)(BGB + ((size_t)slab * 2 + fr) * 2048 + ch) = ws; }
;                 } else {
;                     *(u2*)(Y + (size_t)row * 2048 + ch) = wy;
;                     if (m == 3 && fr >= 14) *(u2*)(VB + ((size_t)slab * 4 + (fr - 14)) * 2048 + ch) = wv;
;                 }
	global_store_dwordx2 v[36:37], v[32:33], off
	v_mov_b32_dpp v38, v24 row_ror:2 row_mask:0xf bank_mask:0xf
	v_mov_b32_dpp v39, v25 row_ror:2 row_mask:0xf bank_mask:0xf
	v_mov_b32_dpp v40, v26 row_ror:2 row_mask:0xf bank_mask:0xf
	v_mov_b32_dpp v41, v27 row_ror:2 row_mask:0xf bank_mask:0xf
	v_pk_mul_f32 v[18:19], v[22:23], v[18:19]
	v_pk_mul_f32 v[16:17], v[20:21], v[16:17]
	v_mov_b32_dpp v32, v24 row_ror:1 row_mask:0xf bank_mask:0xf
	v_mov_b32_dpp v33, v25 row_ror:1 row_mask:0xf bank_mask:0xf
	v_mov_b32_dpp v36, v26 row_ror:1 row_mask:0xf bank_mask:0xf
	v_mov_b32_dpp v37, v27 row_ror:1 row_mask:0xf bank_mask:0xf
	v_pk_mul_f32 v[18:19], v[18:19], v[30:31]
	v_pk_mul_f32 v[16:17], v[16:17], v[28:29]
	v_cndmask_b32_e64 v29, v41, v59, s[4:5]
	v_cndmask_b32_e64 v28, v40, v58, s[4:5]
	v_cndmask_b32_e64 v31, v39, v57, s[4:5]
	v_cndmask_b32_e64 v30, v38, v56, s[4:5]
	v_cndmask_b32_e64 v21, v37, v55, s[2:3]
	v_cndmask_b32_e64 v20, v36, v54, s[2:3]
	v_cndmask_b32_e64 v23, v33, v53, s[2:3]
	v_cndmask_b32_e64 v22, v32, v52, s[2:3]
	v_pk_fma_f32 v[28:29], v[118:119], v[28:29], v[122:123]
	v_pk_fma_f32 v[30:31], v[116:117], v[30:31], v[120:121]
	v_pk_fma_f32 v[20:21], v[110:111], v[20:21], v[28:29]
	v_pk_fma_f32 v[22:23], v[108:109], v[22:23], v[30:31]
	v_pk_fma_f32 v[20:21], v[26:27], v[114:115], v[20:21]
	v_pk_fma_f32 v[22:23], v[24:25], v[112:113], v[22:23]
	v_pk_mul_f32 v[18:19], v[18:19], v[20:21]
	v_pk_mul_f32 v[16:17], v[16:17], v[22:23]
	v_pk_mul_f32 v[14:15], v[14:15], v[162:163] op_sel_hi:[1,0]
	v_cvt_pk_bf16_f32 v16, v16, v17
	v_cvt_pk_bf16_f32 v17, v18, v19
	v_add_co_u32_e32 v18, vcc, s65, v34
	v_pk_mul_f32 v[12:13], v[12:13], v[162:163] op_sel_hi:[1,0]
	s_nop 0
	v_addc_co_u32_e32 v19, vcc, 0, v35, vcc
	global_store_dwordx2 v[18:19], v[16:17], off
	v_pk_mul_f32 v[10:11], v[10:11], v[162:163] op_sel_hi:[1,0]
	v_pk_mul_f32 v[16:17], v[8:9], v[162:163] op_sel_hi:[1,0]
	v_pk_mul_f32 v[0:1], v[0:1], v[162:163] op_sel_hi:[1,0]
	v_pk_mul_f32 v[2:3], v[2:3], v[162:163] op_sel_hi:[1,0]
	v_pk_mul_f32 v[8:9], v[10:11], v[14:15]
	v_pk_mul_f32 v[10:11], v[16:17], v[12:13]
	v_mul_f32_e32 v12, 0xbfb8aa3b, v0
	v_mul_f32_e32 v13, 0xbfb8aa3b, v1
	v_mul_f32_e32 v14, 0xbfb8aa3b, v2
	v_mul_f32_e32 v15, 0xbfb8aa3b, v3
	v_exp_f32_e32 v12, v12
	v_exp_f32_e32 v13, v13
	v_exp_f32_e32 v14, v14
	v_exp_f32_e32 v15, v15
	v_add_f32_e32 v12, 1.0, v12
	v_add_f32_e32 v13, 1.0, v13
	v_add_f32_e32 v14, 1.0, v14
	v_add_f32_e32 v15, 1.0, v15
	v_rcp_f32_e32 v12, v12
	v_rcp_f32_e32 v13, v13
	v_rcp_f32_e32 v14, v14
	v_rcp_f32_e32 v15, v15
	v_pk_mul_f32 v[6:7], v[6:7], v[162:163] op_sel_hi:[1,0]
	v_pk_mul_f32 v[4:5], v[4:5], v[162:163] op_sel_hi:[1,0]
	v_mov_b32_dpp v20, v10 row_ror:2 row_mask:0xf bank_mask:0xf
	v_mov_b32_dpp v21, v11 row_ror:2 row_mask:0xf bank_mask:0xf
	v_mov_b32_dpp v22, v8 row_ror:2 row_mask:0xf bank_mask:0xf
	v_mov_b32_dpp v23, v9 row_ror:2 row_mask:0xf bank_mask:0xf
	v_pk_mul_f32 v[2:3], v[6:7], v[2:3]
	v_pk_mul_f32 v[0:1], v[4:5], v[0:1]
	v_mov_b32_dpp v16, v10 row_ror:1 row_mask:0xf bank_mask:0xf
	v_mov_b32_dpp v17, v11 row_ror:1 row_mask:0xf bank_mask:0xf
	v_mov_b32_dpp v18, v8 row_ror:1 row_mask:0xf bank_mask:0xf
	v_mov_b32_dpp v19, v9 row_ror:1 row_mask:0xf bank_mask:0xf
	v_pk_mul_f32 v[2:3], v[2:3], v[14:15]
	v_pk_mul_f32 v[0:1], v[0:1], v[12:13]
	v_cndmask_b32_e64 v13, v23, v41, s[4:5]
	v_cndmask_b32_e64 v12, v22, v40, s[4:5]
	v_cndmask_b32_e64 v15, v21, v39, s[4:5]
	v_cndmask_b32_e64 v14, v20, v38, s[4:5]
	v_cndmask_b32_e64 v5, v19, v37, s[2:3]
	v_cndmask_b32_e64 v4, v18, v36, s[2:3]
	v_cndmask_b32_e64 v7, v17, v33, s[2:3]
	v_cndmask_b32_e64 v6, v16, v32, s[2:3]
	v_pk_fma_f32 v[12:13], v[118:119], v[12:13], v[122:123]
	v_pk_fma_f32 v[14:15], v[116:117], v[14:15], v[120:121]
	v_pk_fma_f32 v[4:5], v[110:111], v[4:5], v[12:13]
	v_pk_fma_f32 v[6:7], v[108:109], v[6:7], v[14:15]
	v_pk_fma_f32 v[4:5], v[114:115], v[8:9], v[4:5]
	v_pk_fma_f32 v[6:7], v[112:113], v[10:11], v[6:7]
	v_pk_mul_f32 v[2:3], v[2:3], v[4:5]
	v_pk_mul_f32 v[0:1], v[0:1], v[6:7]
	s_nop 0
	v_cvt_pk_bf16_f32 v0, v0, v1
	v_cvt_pk_bf16_f32 v1, v2, v3
	v_add_co_u32_e32 v2, vcc, 0xb0000, v34
	s_nop 1
	v_addc_co_u32_e32 v3, vcc, 0, v35, vcc
	global_store_dwordx2 v[2:3], v[0:1], off
	s_and_saveexec_b64 s[38:39], s[6:7]
	s_cbranch_execz .LBB0_1404
	v_lshl_add_u64 v[2:3], v[152:153], 0, s[8:9]
	v_cvt_pk_bf16_f32 v0, v10, v11
	v_cvt_pk_bf16_f32 v1, v8, v9
	v_lshl_add_u64 v[2:3], v[160:161], 1, v[2:3]
	global_store_dwordx2 v[2:3], v[0:1], off

;     __host__ __device__ bool next(int i, Unit& u) const {
;     ...
;         int wgid = (int)L; { const int q = nwg / NXCD, r = nwg % NXCD, xcd = wgid % NXCD, off = wgid / NXCD; wgid = (xcd < r ? xcd * (q + 1) : r * (q + 1) + (xcd - r) * q) + off; }
;         const int nig = WGM * nN, gid = wgid / nig, fm = gid * WGM, gsz = (nM - fm) < WGM ? (nM - fm) : WGM;
;         u.pm = fm + ((wgid % nig) % gsz); u.pn = (wgid % nig) / gsz; return true;
.LBB0_1547:
	s_ashr_i32 s10, s12, 3
	s_add_i32 s10, s14, s10
	s_ashr_i32 s11, s10, 31
	s_lshr_b32 s11, s11, 26
	s_add_i32 s11, s10, s11
	s_ashr_i32 s12, s11, 6
	s_lshl_b32 s12, s12, 3
	s_andn2_b32 s11, s11, 63
	s_sub_i32 s11, s10, s11
	s_lshr_b32 s10, s11, 3
	s_and_b32 s11, s11, 7
	s_add_i32 s12, s12, s11
